# attention loop: waves 4-7 delayed by s_sleep 2 after each publish barrier (stagger of the two SIMD partners), on top of v12
# speedup vs baseline: 1.0080x; 1.0080x over previous
; __device__ __forceinline__ void expA(f32x16& p0, const float negb) { p0 = p0 + negb; for (int r = 0; r < 16; ++r) p0[r] = __builtin_amdgcn_exp2f(p0[r]); }
; __device__ __forceinline__ int v_st(int k, int c) { const int kk = (k & ~0xC) | ((k & 4) << 1) | ((k & 8) >> 1); return ((kk >> 3) * 4 + (c >> 5)) * 512 + ((kk & 7) * 32 + (c & 31)) * 2; }
; __device__ __forceinline__ int v_rd_base(int lane) { return ((lane & 3) << 3) | (((lane >> 2) & 3) << 6) | (((lane >> 4) & 1) << 5) | (((lane >> 5) & 1) << 8); }
; #define SLOAD(i, k0) do { const unsigned a_ = (unsigned)(k0) * (unsigned)LDK + so0; sr_[i].vs0 = ld8(Kh + (a_ + 256u)); sr_[i].vs1 = ld8(Kh + (a_ + 32u * LDK + 256u)); \
;     sr_[i].ks0 = ld8(Kh + a_); sr_[i].ks1 = ld8(Kh + (a_ + 32u * LDK)); } while (0)
; #define SWRITE(b, i) do { *(bf16x8*)((char*)V_lds + (b) * SHM_V + vst0) = sr_[i].vs0;          \
;     *(bf16x8*)((char*)V_lds + (b) * SHM_V + vst1) = sr_[i].vs1; int kc = sc * 2;               \
;     *(bf16x8*)((char*)K_lds + (b) * SHM_K + KSWZ(sr, kc)) = sr_[i].ks0;                       \
;     *(bf16x8*)((char*)K_lds + (b) * SHM_K + KSWZ(32 + sr, kc)) = sr_[i].ks1; } while (0)
; __device__ __forceinline__ void attn_dense_body(const bf16* __restrict__ Qb, const bf16* __restrict__ Kh, const bf16* __restrict__ Vh,
;                                                 bf16* __restrict__ Ob, int seq, char* lds, const float negb) {
;     ...
;   const bf16* Qw = Qb + (long)(wid * QBLK + r32) * LDQ + hi * 8;
; #pragma unroll
;   for (int d0 = 0; d0 < 8; ++d0) qr[d0] = ld8(Qw + d0 * 16);
;   const int sr = tid >> 4, sc = (tid & 15) * 8, vst0 = v_st(sr, sc), vst1 = v_st(32 + sr, sc);
;   const int vb0 = (int)(uintptr_t)V_lds + v_rd_base(lane);
;   struct { bf16x8 vs0, vs1, ks0, ks1; } sr_[1];
;   const unsigned so0 = (unsigned)(sr * LDK + sc);
;     ...
;   f32x16 pA0, pA1, pB0, pB1; bf16x8 pa0, pa1, pa2, pa3; const int NT = seq / KVBLK;
;   constexpr int SE = 0, SO = 0;
;   SLOAD(SE, 0); asm volatile("s_waitcnt vmcnt(0)" ::: "memory"); SWRITE(0, SE); __syncthreads();
;   qkt(pA0, pA1, K_lds, qr, r32, hi); expA(pA0, negb);
.LBB0_284:
	s_mul_i32 s8, s35, s88
	s_add_i32 s8, s8, s2
	s_cmpk_gt_i32 s8, 0x4ff
	s_mov_b64 s[62:63], -1
	s_cbranch_scc1 .LBB0_283
	s_add_i32 s36, s8, 0xfffffc00
	s_cmpk_lt_i32 s8, 0x400
	s_cselect_b32 s36, s8, s36
	s_cselect_b32 s37, 8, 7
	s_ashr_i32 s37, s36, s37
	s_lshl_b32 s62, s37, 13
	s_addk_i32 s62, 0x2000
	s_lshl_b32 s63, s37, 12
	s_cmpk_lt_i32 s8, 0x400
	s_cselect_b32 s8, 31, 15
	s_cselect_b32 s64, 5, 4
	s_cselect_b32 s37, 0x80, 64
	s_cselect_b32 s80, s62, s63
	s_and_b32 s8, s36, s8
	s_lshr_b32 s36, s36, s64
	s_and_b32 s81, s36, 7
	s_mul_i32 s66, s80, 0xc00
	s_mul_hi_u32 s67, s80, 0xc00
	s_add_u32 s62, s20, s66
	s_addc_u32 s63, s21, s67
	s_lshl_b32 s36, s36, 6
	s_and_b32 s77, s36, 0x100
	s_add_u32 s62, s62, s77
	s_addc_u32 s63, s63, 0
	s_add_u32 s64, s62, 0x800
	s_addc_u32 s65, s63, 0
	s_lshl_b32 s8, s8, 8
	s_add_i32 s8, s80, s8
	s_mul_i32 s80, s8, 0xc00
	s_mul_hi_u32 s36, s8, 0xc00
	s_add_u32 s80, s20, s80
	s_addc_u32 s82, s21, s36
	s_lshl_b32 s36, s81, 7
	s_lshl_b32 s81, s81, 8
	s_add_u32 s80, s80, s81
	s_addc_u32 s81, s82, 0
	v_mov_b32_e32 v167, v149
	v_mov_b32_e32 v171, v149
	v_lshl_add_u64 v[0:1], s[80:81], 0, v[166:167]
	v_lshl_add_u64 v[24:25], s[62:63], 0, v[170:171]
	s_mov_b32 s80, 0x18000
	v_mov_b32_e32 v169, v149
	v_add_co_u32_e32 v12, vcc, s80, v24
	v_lshl_add_u64 v[0:1], v[0:1], 0, v[168:169]
	s_nop 0
	v_addc_co_u32_e32 v13, vcc, 0, v25, vcc
	global_load_dwordx4 v[140:143], v[0:1], off
	global_load_dwordx4 v[136:139], v[0:1], off offset:32
	global_load_dwordx4 v[132:135], v[0:1], off offset:64
	global_load_dwordx4 v[128:131], v[0:1], off offset:96
	global_load_dwordx4 v[124:127], v[0:1], off offset:128
	global_load_dwordx4 v[120:123], v[0:1], off offset:160
	global_load_dwordx4 v[116:119], v[0:1], off offset:192
	global_load_dwordx4 v[112:115], v[0:1], off offset:224
	s_mov_b32 s80, 0x30000
	global_load_dwordx4 v[0:3], v170, s[62:63] offset:2560
	global_load_dwordx4 v[4:7], v[12:13], off offset:2560
	global_load_dwordx4 v[8:11], v170, s[62:63] offset:2048
	s_nop 0
	global_load_dwordx4 v[12:15], v[12:13], off offset:2048
	s_waitcnt vmcnt(0)
	v_add_co_u32_e32 v26, vcc, s80, v24
	s_mov_b32 s80, 0x48000
	s_nop 0
	v_addc_co_u32_e32 v27, vcc, 0, v25, vcc
	v_add_co_u32_e32 v28, vcc, s80, v24
	s_or_b32 s66, s66, s77
	s_nop 0
	v_addc_co_u32_e32 v29, vcc, 0, v25, vcc
	v_mov_b32_e32 v167, 0
	v_lshl_add_u64 v[178:179], v[164:165], 0, s[66:67]
	s_mov_b32 s66, 2
	v_mov_b32_e32 v148, v193
	v_mov_b32_e32 v32, 0
	v_mov_b32_e32 v33, v167
	v_mov_b32_e32 v34, v167
	v_mov_b32_e32 v35, v167
	v_mov_b32_e32 v36, v167
	v_mov_b32_e32 v37, v167
	v_mov_b32_e32 v38, v167
	v_mov_b32_e32 v39, v167
	v_mov_b32_e32 v40, v167
	v_mov_b32_e32 v41, v167
	v_mov_b32_e32 v42, v167
	v_mov_b32_e32 v43, v167
	v_mov_b32_e32 v44, v167
	v_mov_b32_e32 v45, v167
	v_mov_b32_e32 v46, v167
	v_mov_b32_e32 v47, v167
	v_mov_b32_e32 v48, 0
	v_mov_b32_e32 v49, v167
	v_mov_b32_e32 v50, v167
	v_mov_b32_e32 v51, v167
	v_mov_b32_e32 v52, v167
	v_mov_b32_e32 v53, v167
	v_mov_b32_e32 v54, v167
	v_mov_b32_e32 v55, v167
	v_mov_b32_e32 v56, v167
	v_mov_b32_e32 v57, v167
	v_mov_b32_e32 v58, v167
	v_mov_b32_e32 v59, v167
	v_mov_b32_e32 v60, v167
	v_mov_b32_e32 v61, v167
	v_mov_b32_e32 v62, v167
	v_mov_b32_e32 v63, v167
	s_waitcnt vmcnt(3)
	ds_write_b128 v194, v[0:3]
	s_waitcnt vmcnt(2)
	ds_write_b128 v195, v[4:7]
	s_waitcnt vmcnt(1)
	ds_write_b128 v196, v[8:11] offset:32768
	s_waitcnt vmcnt(0)
	ds_write_b128 v197, v[12:15] offset:32768
	s_waitcnt lgkmcnt(0)
	s_barrier
	ds_read_b128 v[0:3], v198 offset:32768
	ds_read_b128 v[16:19], v198 offset:40960
	s_waitcnt lgkmcnt(1)
	v_mfma_f32_32x32x16_bf16 v[0:15], v[0:3], v[140:143], 0
	s_waitcnt lgkmcnt(0)
	v_mfma_f32_32x32x16_bf16 v[64:79], v[16:19], v[140:143], 0
	ds_read_b128 v[16:19], v199 offset:32768
	ds_read_b128 v[20:23], v199 offset:40960
	s_waitcnt lgkmcnt(1)
	v_mfma_f32_32x32x16_bf16 v[0:15], v[16:19], v[136:139], v[0:15]
	s_waitcnt lgkmcnt(0)
	v_mfma_f32_32x32x16_bf16 v[64:79], v[20:23], v[136:139], v[64:79]
	ds_read_b128 v[16:19], v200 offset:32768
	ds_read_b128 v[20:23], v200 offset:40960
	s_waitcnt lgkmcnt(1)
	v_mfma_f32_32x32x16_bf16 v[0:15], v[16:19], v[132:135], v[0:15]
	s_waitcnt lgkmcnt(0)
	v_mfma_f32_32x32x16_bf16 v[64:79], v[20:23], v[132:135], v[64:79]
	ds_read_b128 v[16:19], v201 offset:32768
	ds_read_b128 v[20:23], v201 offset:40960
	s_waitcnt lgkmcnt(1)
	v_mfma_f32_32x32x16_bf16 v[0:15], v[16:19], v[128:131], v[0:15]
	s_waitcnt lgkmcnt(0)
	v_mfma_f32_32x32x16_bf16 v[64:79], v[20:23], v[128:131], v[64:79]
	ds_read_b128 v[16:19], v202 offset:32768
	ds_read_b128 v[20:23], v202 offset:40960
	s_waitcnt lgkmcnt(1)
	v_mfma_f32_32x32x16_bf16 v[0:15], v[16:19], v[124:127], v[0:15]
	s_waitcnt lgkmcnt(0)
	v_mfma_f32_32x32x16_bf16 v[64:79], v[20:23], v[124:127], v[64:79]
	ds_read_b128 v[16:19], v203 offset:32768
	ds_read_b128 v[20:23], v203 offset:40960
	s_waitcnt lgkmcnt(1)
	v_mfma_f32_32x32x16_bf16 v[0:15], v[16:19], v[120:123], v[0:15]
	s_waitcnt lgkmcnt(0)
	v_mfma_f32_32x32x16_bf16 v[64:79], v[20:23], v[120:123], v[64:79]
	ds_read_b128 v[16:19], v204 offset:32768
	ds_read_b128 v[20:23], v204 offset:40960
	s_waitcnt lgkmcnt(1)
	v_mfma_f32_32x32x16_bf16 v[0:15], v[16:19], v[116:119], v[0:15]
	s_waitcnt lgkmcnt(0)
	v_mfma_f32_32x32x16_bf16 v[64:79], v[20:23], v[116:119], v[64:79]
	ds_read_b128 v[16:19], v205 offset:32768
	ds_read_b128 v[20:23], v205 offset:40960
	s_waitcnt lgkmcnt(1)
	v_mfma_f32_32x32x16_bf16 v[0:15], v[16:19], v[112:115], v[0:15]
	global_load_dwordx4 v[16:19], v[26:27], off offset:2560
	s_waitcnt lgkmcnt(0)
; #define SBAR() __builtin_amdgcn_sched_barrier(0)
; __device__ __forceinline__ void expA(f32x16& p0, const float negb) { p0 = p0 + negb; for (int r = 0; r < 16; ++r) p0[r] = __builtin_amdgcn_exp2f(p0[r]); }
; #define SLOAD(i, k0) do { const unsigned a_ = (unsigned)(k0) * (unsigned)LDK + so0; sr_[i].vs0 = ld8(Kh + (a_ + 256u)); sr_[i].vs1 = ld8(Kh + (a_ + 32u * LDK + 256u)); \
;     sr_[i].ks0 = ld8(Kh + a_); sr_[i].ks1 = ld8(Kh + (a_ + 32u * LDK)); } while (0)
; #define SWRITE(b, i) do { *(bf16x8*)((char*)V_lds + (b) * SHM_V + vst0) = sr_[i].vs0;          \
;     *(bf16x8*)((char*)V_lds + (b) * SHM_V + vst1) = sr_[i].vs1; int kc = sc * 2;               \
;     *(bf16x8*)((char*)K_lds + (b) * SHM_K + KSWZ(sr, kc)) = sr_[i].ks0;                       \
;     *(bf16x8*)((char*)K_lds + (b) * SHM_K + KSWZ(32 + sr, kc)) = sr_[i].ks1; } while (0)
; #define SWAIT() asm volatile("s_waitcnt vmcnt(0)" ::: "memory")
; __device__ __forceinline__ void attn_dense_body(const bf16* __restrict__ Qb, const bf16* __restrict__ Kh, const bf16* __restrict__ Vh,
;                                                 bf16* __restrict__ Ob, int seq, char* lds, const float negb) {
;     ...
;   SLOAD(SE, 0); asm volatile("s_waitcnt vmcnt(0)" ::: "memory"); SWRITE(0, SE); __syncthreads();
;   qkt(pA0, pA1, K_lds, qr, r32, hi); expA(pA0, negb);
;   SLOAD(SO, KVBLK);
;   SWAIT(); SWRITE(1, SO); __syncthreads();
;   for (int j = 1; j + 1 < NT; j += 2) {
;     SBAR(); qkt(pB0, pB1, (bf16*)((char*)K_lds + SHM_K), qr, r32, hi);
;     finishSM(pA0, pA1, negb, l_reg, pa0, pa1, pa2, pa3); SBAR();
	v_mfma_f32_32x32x16_bf16 v[64:79], v[20:23], v[112:115], v[64:79]
	global_load_dwordx4 v[20:23], v[28:29], off offset:2560
	s_nop 0
	global_load_dwordx4 v[24:27], v[26:27], off offset:2048
	s_nop 0
	global_load_dwordx4 v[28:31], v[28:29], off offset:2048
	s_nop 3
	v_add_f32_e64 v14, v162, v14
	v_add_f32_e64 v15, v163, v15
	v_pk_add_f32 v[12:13], v[160:161], v[12:13]
	v_pk_add_f32 v[10:11], v[158:159], v[10:11]
	v_pk_add_f32 v[8:9], v[156:157], v[8:9]
	v_pk_add_f32 v[6:7], v[154:155], v[6:7]
	v_pk_add_f32 v[4:5], v[152:153], v[4:5]
	v_pk_add_f32 v[2:3], v[150:151], v[2:3]
	v_pk_add_f32 v[0:1], v[146:147], v[0:1]
	v_exp_f32_e32 v212, v2
	v_exp_f32_e32 v214, v0
	v_exp_f32_e32 v216, v1
	v_exp_f32_e32 v215, v3
	v_exp_f32_e32 v211, v4
	v_exp_f32_e32 v213, v5
	v_exp_f32_e32 v209, v6
	v_exp_f32_e32 v210, v7
	v_exp_f32_e32 v206, v8
	v_exp_f32_e32 v208, v9
	v_exp_f32_e32 v177, v10
	v_exp_f32_e32 v207, v11
	v_exp_f32_e32 v171, v12
	v_exp_f32_e32 v175, v13
	v_exp_f32_e32 v169, v14
	v_exp_f32_e32 v173, v15
	s_waitcnt vmcnt(0)
	s_waitcnt vmcnt(3)
	ds_write_b128 v194, v[16:19] offset:16384
	s_waitcnt vmcnt(2)
	ds_write_b128 v195, v[20:23] offset:16384
	s_waitcnt vmcnt(1)
	ds_write_b128 v196, v[24:27] offset:49152
	s_waitcnt vmcnt(0)
	ds_write_b128 v197, v[28:31] offset:49152
	v_mov_b32_e32 v0, 0
	v_mov_b32_e32 v1, v167
	v_mov_b32_e32 v2, v167
	v_mov_b32_e32 v3, v167
	v_mov_b32_e32 v4, v167
	v_mov_b32_e32 v5, v167
	v_mov_b32_e32 v6, v167
	v_mov_b32_e32 v7, v167
	v_mov_b32_e32 v8, v167
	v_mov_b32_e32 v9, v167
	v_mov_b32_e32 v10, v167
	v_mov_b32_e32 v11, v167
	v_mov_b32_e32 v12, v167
	v_mov_b32_e32 v13, v167
	v_mov_b32_e32 v14, v167
	v_mov_b32_e32 v15, v167
	v_mov_b32_e32 v16, 0
	v_mov_b32_e32 v17, v167
	v_mov_b32_e32 v18, v167
	v_mov_b32_e32 v19, v167
	v_mov_b32_e32 v20, v167
	v_mov_b32_e32 v21, v167
	v_mov_b32_e32 v22, v167
	v_mov_b32_e32 v23, v167
	v_mov_b32_e32 v24, v167
	v_mov_b32_e32 v25, v167
	v_mov_b32_e32 v26, v167
	v_mov_b32_e32 v27, v167
	v_mov_b32_e32 v28, v167
	v_mov_b32_e32 v29, v167
	v_mov_b32_e32 v30, v167
	v_mov_b32_e32 v31, v167
	v_readfirstlane_b32 s98, v145
	s_nop 3
	s_lshr_b32 s98, s98, 8
	s_waitcnt lgkmcnt(0)
	s_barrier
.LBB0_286:
	s_cmp_eq_u32 s98, 0
	s_cbranch_scc1 .Lstg_1a
	s_sleep 2
.Lstg_1a:
	ds_read_b128 v[80:83], v198 offset:49152
	ds_read_b128 v[84:87], v198 offset:57344
	ds_read_b128 v[218:221], v199 offset:49152
	ds_read_b128 v[222:225], v199 offset:57344
	v_pk_add_f32 v[64:65], v[146:147], v[64:65]
	v_pk_add_f32 v[66:67], v[150:151], v[66:67]
	s_waitcnt lgkmcnt(3)
	v_mfma_f32_32x32x16_bf16 v[96:111], v[80:83], v[140:143], 0
	v_exp_f32_e32 v188, v64
	v_add_f32_e32 v64, 0, v214
	v_add_f32_e32 v64, v216, v64
	v_add_f32_e32 v64, v212, v64
	v_add_f32_e32 v64, v215, v64
	v_add_f32_e32 v64, v211, v64
	v_add_f32_e32 v64, v213, v64
	s_waitcnt lgkmcnt(2)
	v_mfma_f32_32x32x16_bf16 v[80:95], v[84:87], v[140:143], 0
	v_add_f32_e32 v64, v209, v64
	v_add_f32_e32 v64, v210, v64
	v_add_f32_e32 v64, v206, v64
	v_add_f32_e32 v64, v208, v64
	v_add_f32_e32 v64, v177, v64
	v_add_f32_e32 v64, v207, v64
	v_add_f32_e32 v64, v171, v64
	s_waitcnt lgkmcnt(1)
	v_mfma_f32_32x32x16_bf16 v[96:111], v[218:221], v[136:139], v[96:111]
	v_exp_f32_e32 v189, v65
	v_add_f32_e32 v64, v175, v64
	v_exp_f32_e32 v217, v66
	v_add_f32_e32 v64, v169, v64
	v_pk_add_f32 v[68:69], v[152:153], v[68:69]
	v_add_f32_e32 v64, v173, v64
	v_add_f32_e32 v64, v188, v64
	s_waitcnt lgkmcnt(0)
	v_mfma_f32_32x32x16_bf16 v[80:95], v[222:225], v[136:139], v[80:95]
	ds_read_b128 v[218:221], v200 offset:49152
	ds_read_b128 v[222:225], v200 offset:57344
	v_add_f32_e64 v70, v154, v70
	v_add_f32_e64 v71, v155, v71
	v_add_f32_e32 v64, v189, v64
	v_add_f32_e32 v64, v217, v64
	v_pk_add_f32 v[72:73], v[156:157], v[72:73]
	v_pk_add_f32 v[74:75], v[158:159], v[74:75]
	v_pk_add_f32 v[76:77], v[160:161], v[76:77]
	s_waitcnt lgkmcnt(1)
	v_mfma_f32_32x32x16_bf16 v[96:111], v[218:221], v[132:135], v[96:111]
	v_exp_f32_e32 v226, v75
	v_exp_f32_e32 v227, v76
	v_pk_add_f32 v[78:79], v[162:163], v[78:79]
	v_exp_f32_e32 v228, v77
	v_exp_f32_e32 v229, v78
	v_exp_f32_e32 v79, v79
	s_waitcnt lgkmcnt(0)
	v_mfma_f32_32x32x16_bf16 v[80:95], v[222:225], v[132:135], v[80:95]
	ds_read_b128 v[218:221], v201 offset:49152
	ds_read_b128 v[222:225], v201 offset:57344
	s_waitcnt lgkmcnt(1)
	v_mfma_f32_32x32x16_bf16 v[96:111], v[218:221], v[128:131], v[96:111]
	s_waitcnt lgkmcnt(0)
	v_mfma_f32_32x32x16_bf16 v[80:95], v[222:225], v[128:131], v[80:95]
	ds_read_b128 v[218:221], v202 offset:49152
	ds_read_b128 v[222:225], v202 offset:57344
	s_waitcnt lgkmcnt(1)
	v_mfma_f32_32x32x16_bf16 v[96:111], v[218:221], v[124:127], v[96:111]
	s_waitcnt lgkmcnt(0)
	v_mfma_f32_32x32x16_bf16 v[80:95], v[222:225], v[124:127], v[80:95]
	ds_read_b128 v[218:221], v203 offset:49152
	ds_read_b128 v[222:225], v203 offset:57344
	s_waitcnt lgkmcnt(1)
	v_mfma_f32_32x32x16_bf16 v[96:111], v[218:221], v[120:123], v[96:111]
	s_waitcnt lgkmcnt(0)
	v_mfma_f32_32x32x16_bf16 v[80:95], v[222:225], v[120:123], v[80:95]
	ds_read_b128 v[218:221], v204 offset:49152
	ds_read_b128 v[222:225], v204 offset:57344
	s_waitcnt lgkmcnt(1)
	v_mfma_f32_32x32x16_bf16 v[96:111], v[218:221], v[116:119], v[96:111]
	s_waitcnt lgkmcnt(0)
	v_mfma_f32_32x32x16_bf16 v[80:95], v[222:225], v[116:119], v[80:95]
	ds_read_b128 v[218:221], v205 offset:49152
	ds_read_b128 v[222:225], v205 offset:57344
	s_waitcnt lgkmcnt(1)
	v_mfma_f32_32x32x16_bf16 v[96:111], v[218:221], v[112:115], v[96:111]
	v_exp_f32_e32 v218, v67
	v_exp_f32_e32 v219, v68
	v_exp_f32_e32 v220, v69
	v_exp_f32_e32 v221, v70
	v_add_f32_e32 v64, v218, v64
	v_add_f32_e32 v64, v219, v64
	v_add_f32_e32 v64, v220, v64
	s_waitcnt lgkmcnt(0)
; #define SBAR() __builtin_amdgcn_sched_barrier(0)
; __device__ __forceinline__ void expA(f32x16& p0, const float negb) { p0 = p0 + negb; for (int r = 0; r < 16; ++r) p0[r] = __builtin_amdgcn_exp2f(p0[r]); }
; #define SLOAD(i, k0) do { const unsigned a_ = (unsigned)(k0) * (unsigned)LDK + so0; sr_[i].vs0 = ld8(Kh + (a_ + 256u)); sr_[i].vs1 = ld8(Kh + (a_ + 32u * LDK + 256u)); \
;     sr_[i].ks0 = ld8(Kh + a_); sr_[i].ks1 = ld8(Kh + (a_ + 32u * LDK)); } while (0)
; #define SWRITE(b, i) do { *(bf16x8*)((char*)V_lds + (b) * SHM_V + vst0) = sr_[i].vs0;          \
;     *(bf16x8*)((char*)V_lds + (b) * SHM_V + vst1) = sr_[i].vs1; int kc = sc * 2;               \
;     *(bf16x8*)((char*)K_lds + (b) * SHM_K + KSWZ(sr, kc)) = sr_[i].ks0;                       \
;     *(bf16x8*)((char*)K_lds + (b) * SHM_K + KSWZ(32 + sr, kc)) = sr_[i].ks1; } while (0)
; #define SWAIT() asm volatile("s_waitcnt vmcnt(0)" ::: "memory")
; __device__ __forceinline__ void finishSM(f32x16& p0, f32x16& p1, const float negb, float& l_reg, bf16x8& pa0, bf16x8& pa1, bf16x8& pa2, bf16x8& pa3) {
;   p1 = p1 + negb; for (int r = 0; r < 16; ++r) p1[r] = __builtin_amdgcn_exp2f(p1[r]);
;   float ps = 0; for (int r = 0; r < 16; ++r) ps += p0[r]; for (int r = 0; r < 16; ++r) ps += p1[r];
;   l_reg += ps;
;     ...
;   PK4(p0, 0, pa0); PK4(p0, 8, pa1); PK4(p1, 0, pa2); PK4(p1, 8, pa3);
; __device__ __forceinline__ void attn_dense_body(const bf16* __restrict__ Qb, const bf16* __restrict__ Kh, const bf16* __restrict__ Vh,
;                                                 bf16* __restrict__ Ob, int seq, char* lds, const float negb) {
;     ...
;     finishSM(pA0, pA1, negb, l_reg, pa0, pa1, pa2, pa3); SBAR();
;     SLOAD(SO, (j + 1) * KVBLK); SBAR();
;     pv_d0(o, vb0, pa0, pa1, pa2, pa3); SBAR(); expA(pB0, negb); SBAR();
;     __syncthreads(); SWAIT(); SWRITE(0, SE); SBAR();
;     __syncthreads();
	v_mfma_f32_32x32x16_bf16 v[80:95], v[222:225], v[112:115], v[80:95]
	v_exp_f32_e32 v222, v71
	v_exp_f32_e32 v223, v72
	v_exp_f32_e32 v224, v73
	v_exp_f32_e32 v225, v74
	v_add_f32_e32 v64, v221, v64
	v_add_f32_e32 v64, v222, v64
	v_add_f32_e32 v64, v223, v64
	v_add_f32_e32 v64, v224, v64
	v_add_f32_e32 v64, v225, v64
	v_add_f32_e32 v64, v226, v64
	v_add_f32_e32 v64, v227, v64
	v_add_f32_e32 v64, v228, v64
	v_add_f32_e32 v64, v229, v64
	v_add_f32_e32 v64, v79, v64
	v_add_f32_e32 v167, v167, v64
	v_cvt_pk_bf16_f32 v64, v214, v216
	v_cvt_pk_bf16_f32 v65, v212, v215
	v_cvt_pk_bf16_f32 v66, v211, v213
	v_cvt_pk_bf16_f32 v67, v209, v210
	v_cvt_pk_bf16_f32 v68, v206, v208
	v_cvt_pk_bf16_f32 v69, v177, v207
	v_cvt_pk_bf16_f32 v70, v171, v175
	v_cvt_pk_bf16_f32 v71, v169, v173
	v_cvt_pk_bf16_f32 v72, v188, v189
	v_cvt_pk_bf16_f32 v73, v217, v218
	v_cvt_pk_bf16_f32 v74, v219, v220
	v_cvt_pk_bf16_f32 v75, v221, v222
	v_cvt_pk_bf16_f32 v76, v223, v224
	v_cvt_pk_bf16_f32 v77, v225, v226
	v_cvt_pk_bf16_f32 v78, v227, v228
	v_cvt_pk_bf16_f32 v79, v229, v79
	s_nop 0
	v_permlane32_swap_b32_e32 v64, v66
	v_permlane32_swap_b32_e32 v65, v67
	v_permlane32_swap_b32_e32 v68, v70
	v_permlane32_swap_b32_e32 v69, v71
	v_permlane32_swap_b32_e32 v72, v74
	v_permlane32_swap_b32_e32 v73, v75
	v_permlane32_swap_b32_e32 v76, v78
	v_permlane32_swap_b32_e32 v77, v79
	s_mov_b32 s67, 0xfffe8000
	v_add_co_u32_e32 v210, vcc, s67, v178
	s_nop 1
	v_addc_co_u32_e32 v211, vcc, -1, v179, vcc
	global_load_dwordx4 v[206:209], v[210:211], off
	s_nop 0
	global_load_dwordx4 v[210:213], v[210:211], off offset:-512
	s_nop 0
	global_load_dwordx4 v[214:217], v[178:179], off
	global_load_dwordx4 v[218:221], v[178:179], off offset:-512
	ds_read_b64_tr_b16 v[222:223], v181 offset:0
	ds_read_b64_tr_b16 v[224:225], v181 offset:0x800
	ds_read_b64_tr_b16 v[226:227], v181 offset:0x1000
	ds_read_b64_tr_b16 v[228:229], v181 offset:0x1800
	ds_read_b64_tr_b16 v[230:231], v181 offset:0x2000
	ds_read_b64_tr_b16 v[232:233], v181 offset:0x2800
	ds_read_b64_tr_b16 v[234:235], v181 offset:0x3000
	ds_read_b64_tr_b16 v[236:237], v181 offset:0x3800
	s_waitcnt lgkmcnt(0)
	s_nop 0
	v_mfma_f32_32x32x16_bf16 v[0:15], v[64:67], v[222:225], v[0:15]
	ds_read_b64_tr_b16 v[222:223], v181 offset:0x200
	ds_read_b64_tr_b16 v[224:225], v181 offset:0xa00
	v_mfma_f32_32x32x16_bf16 v[0:15], v[68:71], v[226:229], v[0:15]
	ds_read_b64_tr_b16 v[226:227], v181 offset:0x1200
	ds_read_b64_tr_b16 v[228:229], v181 offset:0x1a00
	v_mfma_f32_32x32x16_bf16 v[0:15], v[72:75], v[230:233], v[0:15]
	ds_read_b64_tr_b16 v[230:231], v181 offset:0x2200
	ds_read_b64_tr_b16 v[232:233], v181 offset:0x2a00
	ds_read_b64_tr_b16 v[238:239], v181 offset:0x3200
	ds_read_b64_tr_b16 v[240:241], v181 offset:0x3a00
	s_waitcnt lgkmcnt(0)
	v_mfma_f32_32x32x16_bf16 v[0:15], v[76:79], v[234:237], v[0:15]
	v_mfma_f32_32x32x16_bf16 v[16:31], v[64:67], v[222:225], v[16:31]
	ds_read_b64_tr_b16 v[222:223], v181 offset:0x400
	ds_read_b64_tr_b16 v[224:225], v181 offset:0xc00
	v_mfma_f32_32x32x16_bf16 v[16:31], v[68:71], v[226:229], v[16:31]
	ds_read_b64_tr_b16 v[226:227], v181 offset:0x1400
	ds_read_b64_tr_b16 v[228:229], v181 offset:0x1c00
	v_mfma_f32_32x32x16_bf16 v[16:31], v[72:75], v[230:233], v[16:31]
	ds_read_b64_tr_b16 v[230:231], v181 offset:0x2400
	ds_read_b64_tr_b16 v[232:233], v181 offset:0x2c00
	ds_read_b64_tr_b16 v[234:235], v181 offset:0x3400
	ds_read_b64_tr_b16 v[236:237], v181 offset:0x3c00
	s_waitcnt lgkmcnt(0)
	v_mfma_f32_32x32x16_bf16 v[16:31], v[76:79], v[238:241], v[16:31]
	v_mfma_f32_32x32x16_bf16 v[32:47], v[64:67], v[222:225], v[32:47]
	ds_read_b64_tr_b16 v[222:223], v181 offset:0x600
	ds_read_b64_tr_b16 v[224:225], v181 offset:0xe00
	v_mfma_f32_32x32x16_bf16 v[32:47], v[68:71], v[226:229], v[32:47]
	ds_read_b64_tr_b16 v[226:227], v181 offset:0x1600
	ds_read_b64_tr_b16 v[228:229], v181 offset:0x1e00
	v_mfma_f32_32x32x16_bf16 v[32:47], v[72:75], v[230:233], v[32:47]
	ds_read_b64_tr_b16 v[230:231], v181 offset:0x2600
	ds_read_b64_tr_b16 v[232:233], v181 offset:0x2e00
	ds_read_b64_tr_b16 v[238:239], v181 offset:0x3600
	ds_read_b64_tr_b16 v[240:241], v181 offset:0x3e00
	s_waitcnt lgkmcnt(0)
	v_mfma_f32_32x32x16_bf16 v[32:47], v[76:79], v[234:237], v[32:47]
	v_mfma_f32_32x32x16_bf16 v[48:63], v[64:67], v[222:225], v[48:63]
	v_mfma_f32_32x32x16_bf16 v[48:63], v[68:71], v[226:229], v[48:63]
	v_mfma_f32_32x32x16_bf16 v[48:63], v[72:75], v[230:233], v[48:63]
	v_mfma_f32_32x32x16_bf16 v[48:63], v[76:79], v[238:241], v[48:63]
	v_add_f32_e64 v74, v152, v100
	v_add_f32_e64 v75, v153, v101
	v_add_f32_e64 v76, v150, v98
	v_add_f32_e64 v77, v151, v99
	v_add_f32_e64 v78, v146, v96
	v_add_f32_e64 v79, v147, v97
	v_exp_f32_e32 v173, v76
	v_exp_f32_e32 v169, v78
	v_exp_f32_e32 v171, v79
	v_exp_f32_e32 v175, v77
	v_exp_f32_e32 v177, v74
	v_pk_add_f32 v[64:65], v[162:163], v[110:111]
	v_pk_add_f32 v[66:67], v[160:161], v[108:109]
	v_pk_add_f32 v[68:69], v[158:159], v[106:107]
	v_pk_add_f32 v[70:71], v[156:157], v[104:105]
	v_pk_add_f32 v[72:73], v[154:155], v[102:103]
	v_exp_f32_e32 v188, v75
	v_exp_f32_e32 v189, v72
	v_exp_f32_e32 v222, v73
	v_exp_f32_e32 v223, v70
	v_exp_f32_e32 v224, v71
	v_exp_f32_e32 v225, v68
	v_exp_f32_e32 v226, v69
	v_exp_f32_e32 v227, v66
	v_exp_f32_e32 v228, v67
	v_exp_f32_e32 v229, v64
	v_exp_f32_e32 v230, v65
	s_barrier
	s_waitcnt vmcnt(0)
	s_waitcnt vmcnt(3)
	ds_write_b128 v194, v[206:209]
	s_waitcnt vmcnt(1)
	ds_write_b128 v195, v[214:217]
	ds_write_b128 v196, v[210:213] offset:32768
	s_waitcnt vmcnt(0)
	ds_write_b128 v197, v[218:221] offset:32768
	s_waitcnt lgkmcnt(0)
	s_barrier
	s_cmp_eq_u32 s98, 0
	s_cbranch_scc1 .Lstg_1b
	s_sleep 2
; #define SBAR() __builtin_amdgcn_sched_barrier(0)
; __device__ __forceinline__ void expA(f32x16& p0, const float negb) { p0 = p0 + negb; for (int r = 0; r < 16; ++r) p0[r] = __builtin_amdgcn_exp2f(p0[r]); }
; #define SLOAD(i, k0) do { const unsigned a_ = (unsigned)(k0) * (unsigned)LDK + so0; sr_[i].vs0 = ld8(Kh + (a_ + 256u)); sr_[i].vs1 = ld8(Kh + (a_ + 32u * LDK + 256u)); \
;     sr_[i].ks0 = ld8(Kh + a_); sr_[i].ks1 = ld8(Kh + (a_ + 32u * LDK)); } while (0)
; __device__ __forceinline__ void attn_dense_body(const bf16* __restrict__ Qb, const bf16* __restrict__ Kh, const bf16* __restrict__ Vh,
;                                                 bf16* __restrict__ Ob, int seq, char* lds, const float negb) {
;     ...
;     SBAR(); qkt(pA0, pA1, K_lds, qr, r32, hi);
;     finishSM(pB0, pB1, negb, l_reg, pa0, pa1, pa2, pa3); SBAR();
;     SLOAD(SE, (j + 2) * KVBLK); SBAR();
;     pv_d0(o, vb0 + (int)SHM_V, pa0, pa1, pa2, pa3); SBAR(); expA(pA0, negb); SBAR();
.Lstg_1b:
	ds_read_b128 v[64:67], v198 offset:32768
	ds_read_b128 v[68:71], v198 offset:40960
	ds_read_b128 v[206:209], v199 offset:32768
	ds_read_b128 v[210:213], v199 offset:40960
	v_pk_add_f32 v[80:81], v[146:147], v[80:81]
	v_pk_add_f32 v[82:83], v[150:151], v[82:83]
	s_waitcnt lgkmcnt(3)
	v_mfma_f32_32x32x16_bf16 v[96:111], v[64:67], v[140:143], 0
	v_add_f32_e64 v84, v152, v84
	v_add_f32_e64 v85, v153, v85
	v_add_f32_e64 v86, v154, v86
	v_add_f32_e64 v87, v155, v87
	v_add_f32_e64 v88, v156, v88
	v_add_f32_e64 v89, v157, v89
	v_pk_add_f32 v[90:91], v[158:159], v[90:91]
	v_exp_f32_e32 v214, v88
	v_exp_f32_e32 v215, v89
	v_exp_f32_e32 v216, v90
	s_waitcnt lgkmcnt(2)
	v_mfma_f32_32x32x16_bf16 v[64:79], v[68:71], v[140:143], 0
	v_add_f32_e64 v92, v160, v92
	v_add_f32_e64 v93, v161, v93
	v_exp_f32_e32 v217, v91
	v_exp_f32_e32 v218, v92
	v_pk_add_f32 v[94:95], v[162:163], v[94:95]
	v_exp_f32_e32 v219, v93
	v_exp_f32_e32 v220, v94
	v_exp_f32_e32 v95, v95
	s_waitcnt lgkmcnt(1)
	v_mfma_f32_32x32x16_bf16 v[96:111], v[206:209], v[136:139], v[96:111]
	s_waitcnt lgkmcnt(0)
	v_mfma_f32_32x32x16_bf16 v[64:79], v[210:213], v[136:139], v[64:79]
	ds_read_b128 v[206:209], v200 offset:32768
	ds_read_b128 v[210:213], v200 offset:40960
	s_waitcnt lgkmcnt(1)
	v_mfma_f32_32x32x16_bf16 v[96:111], v[206:209], v[132:135], v[96:111]
	s_waitcnt lgkmcnt(0)
	v_mfma_f32_32x32x16_bf16 v[64:79], v[210:213], v[132:135], v[64:79]
	ds_read_b128 v[206:209], v201 offset:32768
	ds_read_b128 v[210:213], v201 offset:40960
	s_waitcnt lgkmcnt(1)
	v_mfma_f32_32x32x16_bf16 v[96:111], v[206:209], v[128:131], v[96:111]
	s_waitcnt lgkmcnt(0)
	v_mfma_f32_32x32x16_bf16 v[64:79], v[210:213], v[128:131], v[64:79]
	ds_read_b128 v[206:209], v202 offset:32768
	ds_read_b128 v[210:213], v202 offset:40960
	s_waitcnt lgkmcnt(1)
	v_mfma_f32_32x32x16_bf16 v[96:111], v[206:209], v[124:127], v[96:111]
	s_waitcnt lgkmcnt(0)
	v_mfma_f32_32x32x16_bf16 v[64:79], v[210:213], v[124:127], v[64:79]
	ds_read_b128 v[206:209], v203 offset:32768
	ds_read_b128 v[210:213], v203 offset:40960
	s_waitcnt lgkmcnt(1)
	v_mfma_f32_32x32x16_bf16 v[96:111], v[206:209], v[120:123], v[96:111]
	s_waitcnt lgkmcnt(0)
	v_mfma_f32_32x32x16_bf16 v[64:79], v[210:213], v[120:123], v[64:79]
	ds_read_b128 v[206:209], v204 offset:32768
	ds_read_b128 v[210:213], v204 offset:40960
	s_waitcnt lgkmcnt(1)
	v_mfma_f32_32x32x16_bf16 v[96:111], v[206:209], v[116:119], v[96:111]
	s_waitcnt lgkmcnt(0)
	v_mfma_f32_32x32x16_bf16 v[64:79], v[210:213], v[116:119], v[64:79]
	ds_read_b128 v[206:209], v205 offset:32768
	ds_read_b128 v[210:213], v205 offset:40960
	s_waitcnt lgkmcnt(1)
	v_mfma_f32_32x32x16_bf16 v[96:111], v[206:209], v[112:115], v[96:111]
	v_exp_f32_e32 v206, v80
	v_add_f32_e32 v80, 0, v169
	v_add_f32_e32 v80, v171, v80
	v_add_f32_e32 v80, v173, v80
	v_add_f32_e32 v80, v175, v80
	v_add_f32_e32 v80, v177, v80
	v_add_f32_e32 v80, v188, v80
	v_add_f32_e32 v80, v189, v80
	v_add_f32_e32 v80, v222, v80
	v_add_f32_e32 v80, v223, v80
	v_add_f32_e32 v80, v224, v80
	v_add_f32_e32 v80, v225, v80
	v_add_f32_e32 v80, v226, v80
	v_add_f32_e32 v80, v227, v80
	v_exp_f32_e32 v207, v81
	v_add_f32_e32 v80, v228, v80
	v_exp_f32_e32 v208, v82
	v_add_f32_e32 v80, v229, v80
	v_exp_f32_e32 v209, v83
	v_add_f32_e32 v80, v230, v80
	s_waitcnt lgkmcnt(0)
	v_mfma_f32_32x32x16_bf16 v[64:79], v[210:213], v[112:115], v[64:79]
	v_exp_f32_e32 v210, v84
	v_add_f32_e32 v80, v206, v80
	v_exp_f32_e32 v211, v85
	v_add_f32_e32 v80, v207, v80
	v_exp_f32_e32 v212, v86
	v_add_f32_e32 v80, v208, v80
	v_exp_f32_e32 v213, v87
	v_add_f32_e32 v80, v209, v80
	v_add_f32_e32 v80, v210, v80
	v_add_f32_e32 v80, v211, v80
	v_add_f32_e32 v80, v212, v80
	v_add_f32_e32 v80, v213, v80
	v_add_f32_e32 v80, v214, v80
	v_add_f32_e32 v80, v215, v80
	v_add_f32_e32 v80, v216, v80
	v_add_f32_e32 v80, v217, v80
	v_add_f32_e32 v80, v218, v80
	v_add_f32_e32 v80, v219, v80
	v_add_f32_e32 v80, v220, v80
	v_add_f32_e32 v80, v95, v80
	v_add_f32_e32 v167, v167, v80
	v_cvt_pk_bf16_f32 v80, v169, v171
	v_cvt_pk_bf16_f32 v81, v173, v175
	v_cvt_pk_bf16_f32 v82, v177, v188
	v_cvt_pk_bf16_f32 v83, v189, v222
	v_cvt_pk_bf16_f32 v84, v223, v224
	v_cvt_pk_bf16_f32 v85, v225, v226
	v_cvt_pk_bf16_f32 v86, v227, v228
	v_cvt_pk_bf16_f32 v87, v229, v230
	v_cvt_pk_bf16_f32 v88, v206, v207
	v_cvt_pk_bf16_f32 v89, v208, v209
	v_cvt_pk_bf16_f32 v90, v210, v211
	v_cvt_pk_bf16_f32 v91, v212, v213
	v_cvt_pk_bf16_f32 v92, v214, v215
	v_cvt_pk_bf16_f32 v93, v216, v217
	v_cvt_pk_bf16_f32 v94, v218, v219
	v_cvt_pk_bf16_f32 v95, v220, v95
	s_nop 0
	v_permlane32_swap_b32_e32 v80, v82
	v_permlane32_swap_b32_e32 v81, v83
	v_permlane32_swap_b32_e32 v84, v86
	v_permlane32_swap_b32_e32 v85, v87
	v_permlane32_swap_b32_e32 v88, v90
	v_permlane32_swap_b32_e32 v89, v91
	v_permlane32_swap_b32_e32 v92, v94
	v_permlane32_swap_b32_e32 v93, v95
	v_add_u32_e32 v210, 0xc100, v148
	v_mov_b32_e32 v211, v149
	v_lshl_add_u64 v[206:207], v[148:149], 1, s[62:63]
	v_add_u32_e32 v208, 0xc000, v148
	v_lshl_add_u64 v[210:211], v[210:211], 1, s[64:65]
	v_mov_b32_e32 v209, v149
	global_load_dwordx4 v[218:221], v[206:207], off offset:2560
	global_load_dwordx4 v[222:225], v[206:207], off offset:2048
	v_lshl_add_u64 v[206:207], v[208:209], 1, s[64:65]
	global_load_dwordx4 v[226:229], v[210:211], off
	global_load_dwordx4 v[230:233], v[206:207], off
	ds_read_b64_tr_b16 v[206:207], v191 offset:0
	ds_read_b64_tr_b16 v[208:209], v191 offset:0x800
	ds_read_b64_tr_b16 v[210:211], v191 offset:0x1000
	ds_read_b64_tr_b16 v[212:213], v191 offset:0x1800
	ds_read_b64_tr_b16 v[214:215], v191 offset:0x2000
	ds_read_b64_tr_b16 v[216:217], v191 offset:0x2800
	ds_read_b64_tr_b16 v[234:235], v191 offset:0x3000
	ds_read_b64_tr_b16 v[236:237], v191 offset:0x3800
	s_waitcnt lgkmcnt(0)
; #define SBAR() __builtin_amdgcn_sched_barrier(0)
; __device__ __forceinline__ void expA(f32x16& p0, const float negb) { p0 = p0 + negb; for (int r = 0; r < 16; ++r) p0[r] = __builtin_amdgcn_exp2f(p0[r]); }
; #define SWRITE(b, i) do { *(bf16x8*)((char*)V_lds + (b) * SHM_V + vst0) = sr_[i].vs0;          \
;     *(bf16x8*)((char*)V_lds + (b) * SHM_V + vst1) = sr_[i].vs1; int kc = sc * 2;               \
;     *(bf16x8*)((char*)K_lds + (b) * SHM_K + KSWZ(sr, kc)) = sr_[i].ks0;                       \
;     *(bf16x8*)((char*)K_lds + (b) * SHM_K + KSWZ(32 + sr, kc)) = sr_[i].ks1; } while (0)
; #define SWAIT() asm volatile("s_waitcnt vmcnt(0)" ::: "memory")
; __device__ __forceinline__ void attn_dense_body(const bf16* __restrict__ Qb, const bf16* __restrict__ Kh, const bf16* __restrict__ Vh,
;                                                 bf16* __restrict__ Ob, int seq, char* lds, const float negb) {
;     ...
;     pv_d0(o, vb0 + (int)SHM_V, pa0, pa1, pa2, pa3); SBAR(); expA(pA0, negb); SBAR();
;     __syncthreads(); SWAIT(); SWRITE(1, SO); SBAR();
;     __syncthreads();
;   }
;   SBAR(); qkt(pB0, pB1, (bf16*)((char*)K_lds + SHM_K), qr, r32, hi);
	s_nop 0
	v_mfma_f32_32x32x16_bf16 v[0:15], v[80:83], v[206:209], v[0:15]
	ds_read_b64_tr_b16 v[206:207], v191 offset:0x200
	ds_read_b64_tr_b16 v[208:209], v191 offset:0xa00
	v_mfma_f32_32x32x16_bf16 v[0:15], v[84:87], v[210:213], v[0:15]
	ds_read_b64_tr_b16 v[210:211], v191 offset:0x1200
	ds_read_b64_tr_b16 v[212:213], v191 offset:0x1a00
	v_mfma_f32_32x32x16_bf16 v[0:15], v[88:91], v[214:217], v[0:15]
	ds_read_b64_tr_b16 v[214:215], v191 offset:0x2200
	ds_read_b64_tr_b16 v[216:217], v191 offset:0x2a00
	ds_read_b64_tr_b16 v[238:239], v191 offset:0x3200
	ds_read_b64_tr_b16 v[240:241], v191 offset:0x3a00
	s_waitcnt lgkmcnt(0)
	v_mfma_f32_32x32x16_bf16 v[0:15], v[92:95], v[234:237], v[0:15]
	v_mfma_f32_32x32x16_bf16 v[16:31], v[80:83], v[206:209], v[16:31]
	ds_read_b64_tr_b16 v[206:207], v191 offset:0x400
	ds_read_b64_tr_b16 v[208:209], v191 offset:0xc00
	v_mfma_f32_32x32x16_bf16 v[16:31], v[84:87], v[210:213], v[16:31]
	ds_read_b64_tr_b16 v[210:211], v191 offset:0x1400
	ds_read_b64_tr_b16 v[212:213], v191 offset:0x1c00
	v_mfma_f32_32x32x16_bf16 v[16:31], v[88:91], v[214:217], v[16:31]
	ds_read_b64_tr_b16 v[214:215], v191 offset:0x2400
	ds_read_b64_tr_b16 v[216:217], v191 offset:0x2c00
	ds_read_b64_tr_b16 v[234:235], v191 offset:0x3400
	ds_read_b64_tr_b16 v[236:237], v191 offset:0x3c00
	s_waitcnt lgkmcnt(0)
	v_mfma_f32_32x32x16_bf16 v[16:31], v[92:95], v[238:241], v[16:31]
	v_mfma_f32_32x32x16_bf16 v[32:47], v[80:83], v[206:209], v[32:47]
	ds_read_b64_tr_b16 v[206:207], v191 offset:0x600
	ds_read_b64_tr_b16 v[208:209], v191 offset:0xe00
	v_mfma_f32_32x32x16_bf16 v[32:47], v[84:87], v[210:213], v[32:47]
	ds_read_b64_tr_b16 v[210:211], v191 offset:0x1600
	ds_read_b64_tr_b16 v[212:213], v191 offset:0x1e00
	v_mfma_f32_32x32x16_bf16 v[32:47], v[88:91], v[214:217], v[32:47]
	ds_read_b64_tr_b16 v[214:215], v191 offset:0x2600
	ds_read_b64_tr_b16 v[216:217], v191 offset:0x2e00
	ds_read_b64_tr_b16 v[238:239], v191 offset:0x3600
	ds_read_b64_tr_b16 v[240:241], v191 offset:0x3e00
	s_waitcnt lgkmcnt(0)
	v_mfma_f32_32x32x16_bf16 v[32:47], v[92:95], v[234:237], v[32:47]
	v_mfma_f32_32x32x16_bf16 v[48:63], v[80:83], v[206:209], v[48:63]
	v_mfma_f32_32x32x16_bf16 v[48:63], v[84:87], v[210:213], v[48:63]
	v_mfma_f32_32x32x16_bf16 v[48:63], v[88:91], v[214:217], v[48:63]
	v_mfma_f32_32x32x16_bf16 v[48:63], v[92:95], v[238:241], v[48:63]
	v_add_f32_e64 v80, v162, v110
	v_add_f32_e64 v81, v163, v111
	v_add_f32_e64 v82, v160, v108
	v_add_f32_e64 v83, v161, v109
	v_add_f32_e64 v84, v158, v106
	v_add_f32_e64 v85, v159, v107
	v_pk_add_f32 v[86:87], v[156:157], v[104:105]
	v_pk_add_f32 v[88:89], v[154:155], v[102:103]
	v_pk_add_f32 v[90:91], v[152:153], v[100:101]
	v_pk_add_f32 v[92:93], v[150:151], v[98:99]
	v_pk_add_f32 v[94:95], v[146:147], v[96:97]
	v_exp_f32_e32 v212, v92
	v_exp_f32_e32 v214, v94
	v_exp_f32_e32 v216, v95
	v_exp_f32_e32 v215, v93
	v_exp_f32_e32 v211, v90
	v_exp_f32_e32 v213, v91
	v_exp_f32_e32 v209, v88
	v_exp_f32_e32 v210, v89
	v_exp_f32_e32 v206, v86
	v_exp_f32_e32 v208, v87
	v_exp_f32_e32 v177, v84
	v_exp_f32_e32 v207, v85
	v_exp_f32_e32 v171, v82
	v_exp_f32_e32 v175, v83
	v_exp_f32_e32 v169, v80
	v_exp_f32_e32 v173, v81
	s_barrier
	s_waitcnt vmcnt(0)
	s_waitcnt vmcnt(3)
	ds_write_b128 v194, v[218:221] offset:16384
	s_waitcnt vmcnt(1)
	ds_write_b128 v195, v[226:229] offset:16384
	ds_write_b128 v196, v[222:225] offset:49152
	s_waitcnt vmcnt(0)
	ds_write_b128 v197, v[230:233] offset:49152
	s_add_i32 s66, s66, 2
	s_mov_b64 s[80:81], 0x60000
	v_add_u32_e32 v148, 0x30000, v148
	s_cmp_ge_u32 s66, s37
	v_lshl_add_u64 v[178:179], v[178:179], 0, s[80:81]
	s_waitcnt lgkmcnt(0)
	s_barrier
	s_cbranch_scc0 .LBB0_286
	ds_read_b128 v[80:83], v198 offset:49152
	ds_read_b128 v[84:87], v198 offset:57344
	v_pk_add_f32 v[64:65], v[146:147], v[64:65]
	v_pk_add_f32 v[66:67], v[150:151], v[66:67]
	v_pk_add_f32 v[68:69], v[152:153], v[68:69]
	s_waitcnt lgkmcnt(1)
	v_mfma_f32_32x32x16_bf16 v[96:111], v[80:83], v[140:143], 0
	v_add_f32_e64 v70, v154, v70
	v_add_f32_e64 v71, v155, v71
	v_add_f32_e64 v72, v156, v72
	v_add_f32_e64 v73, v157, v73
	v_add_f32_e64 v74, v158, v74
	v_add_f32_e64 v75, v159, v75
	v_pk_add_f32 v[76:77], v[160:161], v[76:77]
	v_pk_add_f32 v[78:79], v[162:163], v[78:79]
	s_nop 0
	v_exp_f32_e32 v79, v79
	s_waitcnt lgkmcnt(0)
	v_mfma_f32_32x32x16_bf16 v[80:95], v[84:87], v[140:143], 0
	ds_read_b128 v[140:143], v199 offset:49152
	ds_read_b128 v[218:221], v199 offset:57344
	s_waitcnt lgkmcnt(1)
	v_mfma_f32_32x32x16_bf16 v[96:111], v[140:143], v[136:139], v[96:111]
	s_waitcnt lgkmcnt(0)
	v_mfma_f32_32x32x16_bf16 v[80:95], v[218:221], v[136:139], v[80:95]
	ds_read_b128 v[136:139], v200 offset:49152
	ds_read_b128 v[140:143], v200 offset:57344
	s_waitcnt lgkmcnt(1)
	v_mfma_f32_32x32x16_bf16 v[96:111], v[136:139], v[132:135], v[96:111]
	s_waitcnt lgkmcnt(0)
	v_mfma_f32_32x32x16_bf16 v[80:95], v[140:143], v[132:135], v[80:95]
	ds_read_b128 v[132:135], v201 offset:49152
	ds_read_b128 v[136:139], v201 offset:57344
	s_waitcnt lgkmcnt(1)
	v_mfma_f32_32x32x16_bf16 v[96:111], v[132:135], v[128:131], v[96:111]
	s_waitcnt lgkmcnt(0)
	v_mfma_f32_32x32x16_bf16 v[80:95], v[136:139], v[128:131], v[80:95]
	ds_read_b128 v[128:131], v202 offset:49152
	ds_read_b128 v[132:135], v202 offset:57344
	s_waitcnt lgkmcnt(1)
	v_mfma_f32_32x32x16_bf16 v[96:111], v[128:131], v[124:127], v[96:111]
	s_waitcnt lgkmcnt(0)
	v_mfma_f32_32x32x16_bf16 v[80:95], v[132:135], v[124:127], v[80:95]
	ds_read_b128 v[124:127], v203 offset:49152
	ds_read_b128 v[128:131], v203 offset:57344
	s_waitcnt lgkmcnt(1)
	v_mfma_f32_32x32x16_bf16 v[96:111], v[124:127], v[120:123], v[96:111]
	s_waitcnt lgkmcnt(0)
; #define SBAR() __builtin_amdgcn_sched_barrier(0)
; __device__ __forceinline__ void expA(f32x16& p0, const float negb) { p0 = p0 + negb; for (int r = 0; r < 16; ++r) p0[r] = __builtin_amdgcn_exp2f(p0[r]); }
; __device__ __forceinline__ void attn_dense_body(const bf16* __restrict__ Qb, const bf16* __restrict__ Kh, const bf16* __restrict__ Vh,
;                                                 bf16* __restrict__ Ob, int seq, char* lds, const float negb) {
;     ...
;   SBAR(); qkt(pB0, pB1, (bf16*)((char*)K_lds + SHM_K), qr, r32, hi);
;   finishSM(pA0, pA1, negb, l_reg, pa0, pa1, pa2, pa3); SBAR();
;   pv_d0(o, vb0, pa0, pa1, pa2, pa3); expA(pB0, negb);
	v_mfma_f32_32x32x16_bf16 v[80:95], v[128:131], v[120:123], v[80:95]
	ds_read_b128 v[120:123], v204 offset:49152
	ds_read_b128 v[124:127], v204 offset:57344
	s_waitcnt lgkmcnt(1)
	v_mfma_f32_32x32x16_bf16 v[96:111], v[120:123], v[116:119], v[96:111]
	s_waitcnt lgkmcnt(0)
	v_mfma_f32_32x32x16_bf16 v[80:95], v[124:127], v[116:119], v[80:95]
	ds_read_b128 v[116:119], v205 offset:49152
	ds_read_b128 v[120:123], v205 offset:57344
	v_exp_f32_e32 v124, v76
	v_exp_f32_e32 v125, v77
	v_exp_f32_e32 v126, v78
	s_waitcnt lgkmcnt(1)
	v_mfma_f32_32x32x16_bf16 v[96:111], v[116:119], v[112:115], v[96:111]
	v_exp_f32_e32 v116, v68
	v_exp_f32_e32 v117, v69
	v_exp_f32_e32 v118, v70
	v_exp_f32_e32 v119, v71
	s_waitcnt lgkmcnt(0)
	v_mfma_f32_32x32x16_bf16 v[80:95], v[120:123], v[112:115], v[80:95]
	v_exp_f32_e32 v112, v64
	v_add_f32_e32 v64, 0, v214
	v_add_f32_e32 v64, v216, v64
	v_add_f32_e32 v64, v212, v64
	v_add_f32_e32 v64, v215, v64
	v_add_f32_e32 v64, v211, v64
	v_add_f32_e32 v64, v213, v64
	v_add_f32_e32 v64, v209, v64
	v_add_f32_e32 v64, v210, v64
	v_add_f32_e32 v64, v206, v64
	v_add_f32_e32 v64, v208, v64
	v_add_f32_e32 v64, v177, v64
	v_add_f32_e32 v64, v207, v64
	v_add_f32_e32 v64, v171, v64
	v_exp_f32_e32 v113, v65
	v_add_f32_e32 v64, v175, v64
	v_exp_f32_e32 v114, v66
	v_add_f32_e32 v64, v169, v64
	v_exp_f32_e32 v115, v67
	v_add_f32_e32 v64, v173, v64
	v_add_f32_e32 v64, v112, v64
	v_add_f32_e32 v64, v113, v64
	v_add_f32_e32 v64, v114, v64
	v_add_f32_e32 v64, v115, v64
	v_exp_f32_e32 v120, v72
	v_add_f32_e32 v64, v116, v64
	v_exp_f32_e32 v121, v73
	v_add_f32_e32 v64, v117, v64
	v_exp_f32_e32 v122, v74
	v_add_f32_e32 v64, v118, v64
	v_exp_f32_e32 v123, v75
	v_add_f32_e32 v64, v119, v64
	v_add_f32_e32 v64, v120, v64
	v_add_f32_e32 v64, v121, v64
	v_add_f32_e32 v64, v122, v64
	v_add_f32_e32 v64, v123, v64
	v_add_f32_e32 v64, v124, v64
	v_add_f32_e32 v64, v125, v64
	v_add_f32_e32 v64, v126, v64
	v_add_f32_e32 v64, v79, v64
	v_add_f32_e32 v132, v167, v64
	v_cvt_pk_bf16_f32 v64, v214, v216
	v_cvt_pk_bf16_f32 v65, v212, v215
	v_cvt_pk_bf16_f32 v66, v211, v213
	v_cvt_pk_bf16_f32 v67, v209, v210
	v_cvt_pk_bf16_f32 v68, v206, v208
	v_cvt_pk_bf16_f32 v69, v177, v207
	v_cvt_pk_bf16_f32 v70, v171, v175
	v_cvt_pk_bf16_f32 v71, v169, v173
	s_nop 0
	v_permlane32_swap_b32_e32 v64, v66
	v_permlane32_swap_b32_e32 v65, v67
	v_cvt_pk_bf16_f32 v72, v112, v113
	v_cvt_pk_bf16_f32 v73, v114, v115
	v_cvt_pk_bf16_f32 v74, v116, v117
	v_cvt_pk_bf16_f32 v75, v118, v119
	v_cvt_pk_bf16_f32 v76, v120, v121
	v_cvt_pk_bf16_f32 v77, v122, v123
	v_cvt_pk_bf16_f32 v78, v124, v125
	v_cvt_pk_bf16_f32 v79, v126, v79
	v_permlane32_swap_b32_e32 v68, v70
	v_permlane32_swap_b32_e32 v69, v71
	v_permlane32_swap_b32_e32 v72, v74
	v_permlane32_swap_b32_e32 v73, v75
	v_permlane32_swap_b32_e32 v76, v78
	v_permlane32_swap_b32_e32 v77, v79
	ds_read_b64_tr_b16 v[112:113], v181 offset:0
	ds_read_b64_tr_b16 v[114:115], v181 offset:0x800
	ds_read_b64_tr_b16 v[116:117], v181 offset:0x1000
	ds_read_b64_tr_b16 v[118:119], v181 offset:0x1800
	ds_read_b64_tr_b16 v[120:121], v181 offset:0x2000
	ds_read_b64_tr_b16 v[122:123], v181 offset:0x2800
	ds_read_b64_tr_b16 v[124:125], v181 offset:0x3000
	ds_read_b64_tr_b16 v[126:127], v181 offset:0x3800
	s_waitcnt lgkmcnt(0)
	s_nop 0
	v_mfma_f32_32x32x16_bf16 v[0:15], v[64:67], v[112:115], v[0:15]
	ds_read_b64_tr_b16 v[112:113], v181 offset:0x200
	ds_read_b64_tr_b16 v[114:115], v181 offset:0xa00
	v_mfma_f32_32x32x16_bf16 v[0:15], v[68:71], v[116:119], v[0:15]
	ds_read_b64_tr_b16 v[116:117], v181 offset:0x1200
	ds_read_b64_tr_b16 v[118:119], v181 offset:0x1a00
	v_mfma_f32_32x32x16_bf16 v[0:15], v[72:75], v[120:123], v[0:15]
	ds_read_b64_tr_b16 v[120:121], v181 offset:0x2200
	ds_read_b64_tr_b16 v[122:123], v181 offset:0x2a00
	ds_read_b64_tr_b16 v[128:129], v181 offset:0x3200
	ds_read_b64_tr_b16 v[130:131], v181 offset:0x3a00
	s_waitcnt lgkmcnt(0)
	v_mfma_f32_32x32x16_bf16 v[0:15], v[76:79], v[124:127], v[0:15]
	v_mfma_f32_32x32x16_bf16 v[16:31], v[64:67], v[112:115], v[16:31]
	ds_read_b64_tr_b16 v[112:113], v181 offset:0x400
	ds_read_b64_tr_b16 v[114:115], v181 offset:0xc00
	v_mfma_f32_32x32x16_bf16 v[16:31], v[68:71], v[116:119], v[16:31]
	ds_read_b64_tr_b16 v[116:117], v181 offset:0x1400
	ds_read_b64_tr_b16 v[118:119], v181 offset:0x1c00
	v_mfma_f32_32x32x16_bf16 v[16:31], v[72:75], v[120:123], v[16:31]
	ds_read_b64_tr_b16 v[120:121], v181 offset:0x2400
	ds_read_b64_tr_b16 v[122:123], v181 offset:0x2c00
	ds_read_b64_tr_b16 v[124:125], v181 offset:0x3400
	ds_read_b64_tr_b16 v[126:127], v181 offset:0x3c00
	s_waitcnt lgkmcnt(0)
	v_mfma_f32_32x32x16_bf16 v[16:31], v[76:79], v[128:131], v[16:31]
	v_mfma_f32_32x32x16_bf16 v[32:47], v[64:67], v[112:115], v[32:47]
	ds_read_b64_tr_b16 v[112:113], v181 offset:0x600
	ds_read_b64_tr_b16 v[114:115], v181 offset:0xe00
	v_mfma_f32_32x32x16_bf16 v[32:47], v[68:71], v[116:119], v[32:47]
	ds_read_b64_tr_b16 v[116:117], v181 offset:0x1600
	ds_read_b64_tr_b16 v[118:119], v181 offset:0x1e00
	v_mfma_f32_32x32x16_bf16 v[32:47], v[72:75], v[120:123], v[32:47]
	ds_read_b64_tr_b16 v[120:121], v181 offset:0x2600
	ds_read_b64_tr_b16 v[122:123], v181 offset:0x2e00
	ds_read_b64_tr_b16 v[128:129], v181 offset:0x3600
	ds_read_b64_tr_b16 v[130:131], v181 offset:0x3e00
	s_waitcnt lgkmcnt(0)
; #define SBAR() __builtin_amdgcn_sched_barrier(0)
; __device__ __forceinline__ void expA(f32x16& p0, const float negb) { p0 = p0 + negb; for (int r = 0; r < 16; ++r) p0[r] = __builtin_amdgcn_exp2f(p0[r]); }
; __device__ __forceinline__ void attn_dense_body(const bf16* __restrict__ Qb, const bf16* __restrict__ Kh, const bf16* __restrict__ Vh,
;                                                 bf16* __restrict__ Ob, int seq, char* lds, const float negb) {
;     ...
;   pv_d0(o, vb0, pa0, pa1, pa2, pa3); expA(pB0, negb);
;   __syncthreads();
;   finishSM(pB0, pB1, negb, l_reg, pa0, pa1, pa2, pa3); SBAR();
;   pv_d0(o, vb0 + (int)SHM_V, pa0, pa1, pa2, pa3);
;   { auto rr = __builtin_amdgcn_permlane32_swap(__float_as_uint(l_reg), __float_as_uint(l_reg), false, false); l_reg = __uint_as_float(rr[0]) + __uint_as_float(rr[1]); }
;   if (hi == 0) li_l[r32] = l_reg; asm volatile("s_waitcnt lgkmcnt(0)" ::: "memory");
	v_mfma_f32_32x32x16_bf16 v[32:47], v[76:79], v[124:127], v[32:47]
	v_mfma_f32_32x32x16_bf16 v[48:63], v[64:67], v[112:115], v[48:63]
	v_add_f32_e64 v66, v146, v96
	v_add_f32_e64 v67, v147, v97
	v_add_f32_e64 v64, v150, v98
	v_add_f32_e64 v65, v151, v99
	v_exp_f32_e32 v96, v66
	v_exp_f32_e32 v97, v67
	v_exp_f32_e32 v98, v64
	v_pk_add_f32 v[100:101], v[152:153], v[100:101]
	v_exp_f32_e32 v99, v65
	v_mfma_f32_32x32x16_bf16 v[48:63], v[68:71], v[116:119], v[48:63]
	v_add_f32_e64 v64, v162, v94
	v_add_f32_e64 v65, v163, v95
	v_exp_f32_e32 v100, v100
	v_pk_add_f32 v[68:69], v[158:159], v[90:91]
	v_exp_f32_e32 v90, v64
	v_add_f32_e32 v64, 0, v96
	v_pk_add_f32 v[102:103], v[154:155], v[102:103]
	v_exp_f32_e32 v101, v101
	v_add_f32_e32 v64, v97, v64
	v_exp_f32_e32 v102, v102
	v_add_f32_e32 v64, v98, v64
	v_pk_add_f32 v[104:105], v[156:157], v[104:105]
	v_exp_f32_e32 v103, v103
	v_mfma_f32_32x32x16_bf16 v[48:63], v[72:75], v[120:123], v[48:63]
	v_add_f32_e32 v64, v99, v64
	v_exp_f32_e32 v104, v104
	v_add_f32_e32 v64, v100, v64
	v_pk_add_f32 v[106:107], v[158:159], v[106:107]
	v_exp_f32_e32 v105, v105
	v_add_f32_e32 v64, v101, v64
	v_exp_f32_e32 v106, v106
	v_add_f32_e32 v64, v102, v64
	v_pk_add_f32 v[108:109], v[160:161], v[108:109]
	v_exp_f32_e32 v107, v107
	v_add_f32_e32 v64, v103, v64
	v_exp_f32_e32 v108, v108
	v_add_f32_e32 v64, v104, v64
	v_pk_add_f32 v[110:111], v[162:163], v[110:111]
	v_exp_f32_e32 v109, v109
	v_add_f32_e32 v64, v105, v64
	v_exp_f32_e32 v110, v110
	v_add_f32_e32 v64, v106, v64
	v_exp_f32_e32 v111, v111
	v_mfma_f32_32x32x16_bf16 v[48:63], v[76:79], v[128:131], v[48:63]
	v_add_f32_e64 v78, v146, v80
	v_add_f32_e64 v79, v147, v81
	v_add_f32_e32 v64, v107, v64
	v_exp_f32_e32 v78, v78
	v_add_f32_e32 v64, v108, v64
	v_pk_add_f32 v[76:77], v[150:151], v[82:83]
	v_exp_f32_e32 v79, v79
	v_add_f32_e32 v64, v109, v64
	v_exp_f32_e32 v76, v76
	v_add_f32_e32 v64, v110, v64
	v_pk_add_f32 v[74:75], v[152:153], v[84:85]
	v_exp_f32_e32 v77, v77
	v_add_f32_e32 v64, v111, v64
	v_exp_f32_e32 v80, v74
	v_add_f32_e32 v64, v78, v64
	v_pk_add_f32 v[72:73], v[154:155], v[86:87]
	v_exp_f32_e32 v81, v75
	v_add_f32_e32 v64, v79, v64
	v_exp_f32_e32 v82, v72
	v_add_f32_e32 v64, v76, v64
	v_pk_add_f32 v[70:71], v[156:157], v[88:89]
	v_exp_f32_e32 v83, v73
	v_add_f32_e32 v64, v77, v64
	v_exp_f32_e32 v84, v70
	v_add_f32_e32 v64, v80, v64
	v_exp_f32_e32 v85, v71
	v_add_f32_e32 v64, v81, v64
	v_exp_f32_e32 v86, v68
	v_add_f32_e32 v64, v82, v64
	v_pk_add_f32 v[66:67], v[160:161], v[92:93]
	v_exp_f32_e32 v87, v69
	v_add_f32_e32 v64, v83, v64
	v_exp_f32_e32 v88, v66
	v_add_f32_e32 v64, v84, v64
	v_exp_f32_e32 v89, v67
	v_add_f32_e32 v64, v85, v64
	v_add_f32_e32 v64, v86, v64
	v_exp_f32_e32 v65, v65
	v_add_f32_e32 v64, v87, v64
	v_add_f32_e32 v64, v88, v64
	v_add_f32_e32 v64, v89, v64
	v_add_f32_e32 v64, v90, v64
	v_add_f32_e32 v64, v65, v64
	s_barrier
	v_add_f32_e32 v64, v132, v64
	v_cvt_pk_bf16_f32 v66, v96, v97
	v_cvt_pk_bf16_f32 v67, v98, v99
	v_cvt_pk_bf16_f32 v68, v100, v101
	v_cvt_pk_bf16_f32 v69, v102, v103
	v_cvt_pk_bf16_f32 v70, v104, v105
	v_cvt_pk_bf16_f32 v71, v106, v107
	v_cvt_pk_bf16_f32 v72, v108, v109
	v_cvt_pk_bf16_f32 v73, v110, v111
	v_cvt_pk_bf16_f32 v74, v78, v79
	v_cvt_pk_bf16_f32 v75, v76, v77
	v_cvt_pk_bf16_f32 v76, v80, v81
	v_cvt_pk_bf16_f32 v77, v82, v83
	v_cvt_pk_bf16_f32 v78, v84, v85
	v_cvt_pk_bf16_f32 v79, v86, v87
	v_cvt_pk_bf16_f32 v80, v88, v89
	v_cvt_pk_bf16_f32 v81, v90, v65
	s_nop 0
	v_permlane32_swap_b32_e32 v66, v68
	v_permlane32_swap_b32_e32 v67, v69
	v_permlane32_swap_b32_e32 v70, v72
	v_permlane32_swap_b32_e32 v71, v73
	v_permlane32_swap_b32_e32 v74, v76
	v_permlane32_swap_b32_e32 v75, v77
	v_permlane32_swap_b32_e32 v78, v80
	v_permlane32_swap_b32_e32 v79, v81
	ds_read_b64_tr_b16 v[82:83], v191 offset:0
	ds_read_b64_tr_b16 v[84:85], v191 offset:0x800
	ds_read_b64_tr_b16 v[86:87], v191 offset:0x1000
	ds_read_b64_tr_b16 v[88:89], v191 offset:0x1800
	ds_read_b64_tr_b16 v[90:91], v191 offset:0x2000
	ds_read_b64_tr_b16 v[92:93], v191 offset:0x2800
	ds_read_b64_tr_b16 v[94:95], v191 offset:0x3000
	ds_read_b64_tr_b16 v[96:97], v191 offset:0x3800
	s_waitcnt lgkmcnt(0)
	s_nop 0
	v_mfma_f32_32x32x16_bf16 v[0:15], v[66:69], v[82:85], v[0:15]
	ds_read_b64_tr_b16 v[82:83], v191 offset:0x200
	ds_read_b64_tr_b16 v[84:85], v191 offset:0xa00
	v_mfma_f32_32x32x16_bf16 v[0:15], v[70:73], v[86:89], v[0:15]
	ds_read_b64_tr_b16 v[86:87], v191 offset:0x1200
	ds_read_b64_tr_b16 v[88:89], v191 offset:0x1a00
	v_mfma_f32_32x32x16_bf16 v[0:15], v[74:77], v[90:93], v[0:15]
	ds_read_b64_tr_b16 v[90:91], v191 offset:0x2200
	ds_read_b64_tr_b16 v[92:93], v191 offset:0x2a00
	ds_read_b64_tr_b16 v[98:99], v191 offset:0x3200
	ds_read_b64_tr_b16 v[100:101], v191 offset:0x3a00
	s_waitcnt lgkmcnt(0)
	v_mfma_f32_32x32x16_bf16 v[0:15], v[78:81], v[94:97], v[0:15]
	v_mfma_f32_32x32x16_bf16 v[16:31], v[66:69], v[82:85], v[16:31]
	ds_read_b64_tr_b16 v[82:83], v191 offset:0x400
	ds_read_b64_tr_b16 v[84:85], v191 offset:0xc00
	v_mfma_f32_32x32x16_bf16 v[16:31], v[70:73], v[86:89], v[16:31]
	ds_read_b64_tr_b16 v[86:87], v191 offset:0x1400
	ds_read_b64_tr_b16 v[88:89], v191 offset:0x1c00
	v_mfma_f32_32x32x16_bf16 v[16:31], v[74:77], v[90:93], v[16:31]
	ds_read_b64_tr_b16 v[90:91], v191 offset:0x2400
	ds_read_b64_tr_b16 v[92:93], v191 offset:0x2c00
	ds_read_b64_tr_b16 v[94:95], v191 offset:0x3400
	ds_read_b64_tr_b16 v[96:97], v191 offset:0x3c00
	s_waitcnt lgkmcnt(0)
	v_mfma_f32_32x32x16_bf16 v[16:31], v[78:81], v[98:101], v[16:31]
	v_mfma_f32_32x32x16_bf16 v[32:47], v[66:69], v[82:85], v[32:47]
	ds_read_b64_tr_b16 v[82:83], v191 offset:0x600
	ds_read_b64_tr_b16 v[84:85], v191 offset:0xe00
	v_mfma_f32_32x32x16_bf16 v[32:47], v[70:73], v[86:89], v[32:47]
	ds_read_b64_tr_b16 v[86:87], v191 offset:0x1600
	ds_read_b64_tr_b16 v[88:89], v191 offset:0x1e00
	v_mfma_f32_32x32x16_bf16 v[32:47], v[74:77], v[90:93], v[32:47]
	ds_read_b64_tr_b16 v[90:91], v191 offset:0x2600
	ds_read_b64_tr_b16 v[92:93], v191 offset:0x2e00
	ds_read_b64_tr_b16 v[98:99], v191 offset:0x3600
	ds_read_b64_tr_b16 v[100:101], v191 offset:0x3e00
	s_waitcnt lgkmcnt(0)
	v_mfma_f32_32x32x16_bf16 v[32:47], v[78:81], v[94:97], v[32:47]
	v_mfma_f32_32x32x16_bf16 v[48:63], v[66:69], v[82:85], v[48:63]
	v_mov_b32_e32 v65, v64
	s_nop 1
	v_permlane32_swap_b32_e32 v64, v65
	v_mfma_f32_32x32x16_bf16 v[48:63], v[70:73], v[86:89], v[48:63]
	v_mfma_f32_32x32x16_bf16 v[48:63], v[74:77], v[90:93], v[48:63]
	v_mfma_f32_32x32x16_bf16 v[48:63], v[78:81], v[98:101], v[48:63]
	s_and_saveexec_b64 s[62:63], s[4:5]
	s_cbranch_execz .LBB0_282
	v_add_f32_e32 v64, v64, v65
	ds_write_b32 v192, v64
	s_branch .LBB0_282

; __device__ __forceinline__ int v_st(int k, int c) { const int kk = (k & ~0xC) | ((k & 4) << 1) | ((k & 8) >> 1); return ((kk >> 3) * 4 + (c >> 5)) * 512 + ((kk & 7) * 32 + (c & 31)) * 2; }
; __device__ __forceinline__ int v_rd_base(int lane) { return ((lane & 3) << 3) | (((lane >> 2) & 3) << 6) | (((lane >> 4) & 1) << 5) | (((lane >> 5) & 1) << 8); }
; #define SLOAD(i, k0) do { const unsigned a_ = (unsigned)(k0) * (unsigned)LDK + so0; sr_[i].vs0 = ld8(Kh + (a_ + 256u)); sr_[i].vs1 = ld8(Kh + (a_ + 32u * LDK + 256u)); \
;     sr_[i].ks0 = ld8(Kh + a_); sr_[i].ks1 = ld8(Kh + (a_ + 32u * LDK)); } while (0)
; #define SWRITE(b, i) do { *(bf16x8*)((char*)V_lds + (b) * SHM_V + vst0) = sr_[i].vs0;          \
;     *(bf16x8*)((char*)V_lds + (b) * SHM_V + vst1) = sr_[i].vs1; int kc = sc * 2;               \
;     *(bf16x8*)((char*)K_lds + (b) * SHM_K + KSWZ(sr, kc)) = sr_[i].ks0;                       \
;     *(bf16x8*)((char*)K_lds + (b) * SHM_K + KSWZ(32 + sr, kc)) = sr_[i].ks1; } while (0)
; __device__ __forceinline__ void attn_dense_body(const bf16* __restrict__ Qb, const bf16* __restrict__ Kh, const bf16* __restrict__ Vh,
;                                                 bf16* __restrict__ Ob, int seq, char* lds, const float negb) {
;     ...
;   const bf16* Qw = Qb + (long)(wid * QBLK + r32) * LDQ + hi * 8;
; #pragma unroll
;   for (int d0 = 0; d0 < 8; ++d0) qr[d0] = ld8(Qw + d0 * 16);
;   const int sr = tid >> 4, sc = (tid & 15) * 8, vst0 = v_st(sr, sc), vst1 = v_st(32 + sr, sc);
;   const int vb0 = (int)(uintptr_t)V_lds + v_rd_base(lane);
;   struct { bf16x8 vs0, vs1, ks0, ks1; } sr_[1];
;   const unsigned so0 = (unsigned)(sr * LDK + sc);
;     ...
;   f32x16 pA0, pA1, pB0, pB1; bf16x8 pa0, pa1, pa2, pa3; const int NT = seq / KVBLK;
;   constexpr int SE = 0, SO = 0;
;   SLOAD(SE, 0); asm volatile("s_waitcnt vmcnt(0)" ::: "memory"); SWRITE(0, SE); __syncthreads();
.LBB0_514:
	s_mul_i32 s4, s79, s88
	s_add_i32 s4, s4, s2
	s_cmpk_gt_i32 s4, 0x4ff
	s_mov_b64 s[60:61], -1
	s_cbranch_scc1 .LBB0_513
	s_add_i32 s60, s4, 0xfffffc00
	s_cmpk_lt_i32 s4, 0x400
	s_cselect_b32 s60, s4, s60
	s_cselect_b32 s61, 8, 7
	s_ashr_i32 s61, s60, s61
	s_lshl_b32 s62, s61, 13
	s_addk_i32 s62, 0x2000
	s_lshl_b32 s61, s61, 12
	s_cmpk_lt_i32 s4, 0x400
	s_cselect_b32 s4, 31, 15
	s_cselect_b32 s63, 5, 4
	s_cselect_b32 s82, 0x80, 64
	s_cselect_b32 s81, s62, s61
	s_and_b32 s4, s60, s4
	s_lshr_b32 s60, s60, s63
	s_and_b32 s84, s60, 7
	s_mul_i32 s64, s81, 0xc00
	s_mul_hi_u32 s65, s81, 0xc00
	s_add_u32 s61, s20, s64
	s_addc_u32 s62, s21, s65
	s_lshl_b32 s60, s60, 6
	s_and_b32 s83, s60, 0x100
	s_add_u32 s60, s61, s83
	s_addc_u32 s61, s62, 0
	s_add_u32 s62, s60, 0x800
	s_addc_u32 s63, s61, 0
	s_lshl_b32 s4, s4, 8
	s_add_i32 s4, s81, s4
	s_mul_i32 s85, s4, 0xc00
	s_mul_hi_u32 s81, s4, 0xc00
	s_add_u32 s85, s20, s85
	s_addc_u32 s86, s21, s81
	s_lshl_b32 s81, s84, 7
	s_lshl_b32 s84, s84, 8
	s_add_u32 s84, s85, s84
	v_mov_b32_e32 v171, v149
	s_addc_u32 s85, s86, 0
	v_mov_b32_e32 v167, v149
	v_lshl_add_u64 v[24:25], s[60:61], 0, v[170:171]
	v_lshl_add_u64 v[0:1], s[84:85], 0, v[166:167]
	v_mov_b32_e32 v169, v149
	v_add_co_u32_e32 v12, vcc, s28, v24
	v_lshl_add_u64 v[0:1], v[0:1], 0, v[168:169]
	s_nop 0
	v_addc_co_u32_e32 v13, vcc, 0, v25, vcc
	global_load_dwordx4 v[140:143], v[0:1], off
	global_load_dwordx4 v[136:139], v[0:1], off offset:32
	global_load_dwordx4 v[132:135], v[0:1], off offset:64
	global_load_dwordx4 v[128:131], v[0:1], off offset:96
	global_load_dwordx4 v[124:127], v[0:1], off offset:128
	global_load_dwordx4 v[120:123], v[0:1], off offset:160
	global_load_dwordx4 v[116:119], v[0:1], off offset:192
	global_load_dwordx4 v[112:115], v[0:1], off offset:224
	v_add_co_u32_e32 v26, vcc, s29, v24
	global_load_dwordx4 v[0:3], v170, s[60:61] offset:2560
	global_load_dwordx4 v[4:7], v[12:13], off offset:2560
	global_load_dwordx4 v[8:11], v170, s[60:61] offset:2048
	s_nop 0
	global_load_dwordx4 v[12:15], v[12:13], off offset:2048
	s_waitcnt vmcnt(0)
	v_addc_co_u32_e32 v27, vcc, 0, v25, vcc
	s_mov_b32 s84, 0x48000
	v_add_co_u32_e32 v28, vcc, s84, v24
	s_or_b32 s64, s64, s83
	s_nop 0
	v_addc_co_u32_e32 v29, vcc, 0, v25, vcc
	v_mov_b32_e32 v167, 0
	v_lshl_add_u64 v[178:179], v[164:165], 0, s[64:65]
	s_mov_b32 s64, 2
	v_mov_b32_e32 v148, v193
	v_mov_b32_e32 v32, 0
	v_mov_b32_e32 v33, v167
	v_mov_b32_e32 v34, v167
	v_mov_b32_e32 v35, v167
	v_mov_b32_e32 v36, v167
	v_mov_b32_e32 v37, v167
	v_mov_b32_e32 v38, v167
	v_mov_b32_e32 v39, v167
	v_mov_b32_e32 v40, v167
	v_mov_b32_e32 v41, v167
	v_mov_b32_e32 v42, v167
	v_mov_b32_e32 v43, v167
	v_mov_b32_e32 v44, v167
	v_mov_b32_e32 v45, v167
	v_mov_b32_e32 v46, v167
	v_mov_b32_e32 v47, v167
	v_mov_b32_e32 v48, 0
	v_mov_b32_e32 v49, v167
	v_mov_b32_e32 v50, v167
	v_mov_b32_e32 v51, v167
	v_mov_b32_e32 v52, v167
	v_mov_b32_e32 v53, v167
	v_mov_b32_e32 v54, v167
	v_mov_b32_e32 v55, v167
	v_mov_b32_e32 v56, v167
	v_mov_b32_e32 v57, v167
	v_mov_b32_e32 v58, v167
	v_mov_b32_e32 v59, v167
	v_mov_b32_e32 v60, v167
	v_mov_b32_e32 v61, v167
	v_mov_b32_e32 v62, v167
	v_mov_b32_e32 v63, v167
	s_waitcnt vmcnt(3)
	ds_write_b128 v194, v[0:3]
	s_waitcnt vmcnt(2)
	ds_write_b128 v195, v[4:7]
	s_waitcnt vmcnt(1)
	ds_write_b128 v196, v[8:11] offset:32768
	s_waitcnt vmcnt(0)
	ds_write_b128 v197, v[12:15] offset:32768
	s_waitcnt lgkmcnt(0)
	s_barrier
; __device__ __forceinline__ void expA(f32x16& p0, const float negb) { p0 = p0 + negb; for (int r = 0; r < 16; ++r) p0[r] = __builtin_amdgcn_exp2f(p0[r]); }
; #define SLOAD(i, k0) do { const unsigned a_ = (unsigned)(k0) * (unsigned)LDK + so0; sr_[i].vs0 = ld8(Kh + (a_ + 256u)); sr_[i].vs1 = ld8(Kh + (a_ + 32u * LDK + 256u)); \
;     sr_[i].ks0 = ld8(Kh + a_); sr_[i].ks1 = ld8(Kh + (a_ + 32u * LDK)); } while (0)
; #define SWRITE(b, i) do { *(bf16x8*)((char*)V_lds + (b) * SHM_V + vst0) = sr_[i].vs0;          \
;     *(bf16x8*)((char*)V_lds + (b) * SHM_V + vst1) = sr_[i].vs1; int kc = sc * 2;               \
;     *(bf16x8*)((char*)K_lds + (b) * SHM_K + KSWZ(sr, kc)) = sr_[i].ks0;                       \
;     *(bf16x8*)((char*)K_lds + (b) * SHM_K + KSWZ(32 + sr, kc)) = sr_[i].ks1; } while (0)
; #define SWAIT() asm volatile("s_waitcnt vmcnt(0)" ::: "memory")
; __device__ __forceinline__ void attn_dense_body(const bf16* __restrict__ Qb, const bf16* __restrict__ Kh, const bf16* __restrict__ Vh,
;                                                 bf16* __restrict__ Ob, int seq, char* lds, const float negb) {
;     ...
;   qkt(pA0, pA1, K_lds, qr, r32, hi); expA(pA0, negb);
;   SLOAD(SO, KVBLK);
;   SWAIT(); SWRITE(1, SO); __syncthreads();
	ds_read_b128 v[0:3], v198 offset:32768
	ds_read_b128 v[16:19], v198 offset:40960
	s_waitcnt lgkmcnt(1)
	v_mfma_f32_32x32x16_bf16 v[0:15], v[0:3], v[140:143], 0
	s_waitcnt lgkmcnt(0)
	v_mfma_f32_32x32x16_bf16 v[64:79], v[16:19], v[140:143], 0
	ds_read_b128 v[16:19], v199 offset:32768
	ds_read_b128 v[20:23], v199 offset:40960
	s_waitcnt lgkmcnt(1)
	v_mfma_f32_32x32x16_bf16 v[0:15], v[16:19], v[136:139], v[0:15]
	s_waitcnt lgkmcnt(0)
	v_mfma_f32_32x32x16_bf16 v[64:79], v[20:23], v[136:139], v[64:79]
	ds_read_b128 v[16:19], v200 offset:32768
	ds_read_b128 v[20:23], v200 offset:40960
	s_waitcnt lgkmcnt(1)
	v_mfma_f32_32x32x16_bf16 v[0:15], v[16:19], v[132:135], v[0:15]
	s_waitcnt lgkmcnt(0)
	v_mfma_f32_32x32x16_bf16 v[64:79], v[20:23], v[132:135], v[64:79]
	ds_read_b128 v[16:19], v201 offset:32768
	ds_read_b128 v[20:23], v201 offset:40960
	s_waitcnt lgkmcnt(1)
	v_mfma_f32_32x32x16_bf16 v[0:15], v[16:19], v[128:131], v[0:15]
	s_waitcnt lgkmcnt(0)
	v_mfma_f32_32x32x16_bf16 v[64:79], v[20:23], v[128:131], v[64:79]
	ds_read_b128 v[16:19], v202 offset:32768
	ds_read_b128 v[20:23], v202 offset:40960
	s_waitcnt lgkmcnt(1)
	v_mfma_f32_32x32x16_bf16 v[0:15], v[16:19], v[124:127], v[0:15]
	s_waitcnt lgkmcnt(0)
	v_mfma_f32_32x32x16_bf16 v[64:79], v[20:23], v[124:127], v[64:79]
	ds_read_b128 v[16:19], v203 offset:32768
	ds_read_b128 v[20:23], v203 offset:40960
	s_waitcnt lgkmcnt(1)
	v_mfma_f32_32x32x16_bf16 v[0:15], v[16:19], v[120:123], v[0:15]
	s_waitcnt lgkmcnt(0)
	v_mfma_f32_32x32x16_bf16 v[64:79], v[20:23], v[120:123], v[64:79]
	ds_read_b128 v[16:19], v204 offset:32768
	ds_read_b128 v[20:23], v204 offset:40960
	s_waitcnt lgkmcnt(1)
	v_mfma_f32_32x32x16_bf16 v[0:15], v[16:19], v[116:119], v[0:15]
	s_waitcnt lgkmcnt(0)
	v_mfma_f32_32x32x16_bf16 v[64:79], v[20:23], v[116:119], v[64:79]
	ds_read_b128 v[16:19], v205 offset:32768
	ds_read_b128 v[20:23], v205 offset:40960
	s_waitcnt lgkmcnt(1)
	v_mfma_f32_32x32x16_bf16 v[0:15], v[16:19], v[112:115], v[0:15]
	global_load_dwordx4 v[16:19], v[26:27], off offset:2560
	s_waitcnt lgkmcnt(0)
	v_mfma_f32_32x32x16_bf16 v[64:79], v[20:23], v[112:115], v[64:79]
	global_load_dwordx4 v[20:23], v[28:29], off offset:2560
	s_nop 0
	global_load_dwordx4 v[24:27], v[26:27], off offset:2048
	s_nop 0
	global_load_dwordx4 v[28:31], v[28:29], off offset:2048
	s_nop 3
	v_add_f32_e64 v14, v162, v14
	v_add_f32_e64 v15, v163, v15
	v_pk_add_f32 v[12:13], v[160:161], v[12:13]
	v_pk_add_f32 v[10:11], v[158:159], v[10:11]
	v_pk_add_f32 v[8:9], v[156:157], v[8:9]
	v_pk_add_f32 v[6:7], v[154:155], v[6:7]
	v_pk_add_f32 v[4:5], v[152:153], v[4:5]
	v_pk_add_f32 v[2:3], v[150:151], v[2:3]
	v_pk_add_f32 v[0:1], v[146:147], v[0:1]
	v_exp_f32_e32 v212, v2
	v_exp_f32_e32 v214, v0
	v_exp_f32_e32 v216, v1
	v_exp_f32_e32 v215, v3
	v_exp_f32_e32 v211, v4
	v_exp_f32_e32 v213, v5
	v_exp_f32_e32 v209, v6
	v_exp_f32_e32 v210, v7
	v_exp_f32_e32 v206, v8
	v_exp_f32_e32 v208, v9
	v_exp_f32_e32 v177, v10
	v_exp_f32_e32 v207, v11
	v_exp_f32_e32 v171, v12
	v_exp_f32_e32 v175, v13
	v_exp_f32_e32 v169, v14
	v_exp_f32_e32 v173, v15
	s_waitcnt vmcnt(0)
	s_waitcnt vmcnt(3)
	ds_write_b128 v194, v[16:19] offset:16384
	s_waitcnt vmcnt(2)
	ds_write_b128 v195, v[20:23] offset:16384
	s_waitcnt vmcnt(1)
	ds_write_b128 v196, v[24:27] offset:49152
	s_waitcnt vmcnt(0)
	ds_write_b128 v197, v[28:31] offset:49152
	v_mov_b32_e32 v0, 0
	v_mov_b32_e32 v1, v167
	v_mov_b32_e32 v2, v167
	v_mov_b32_e32 v3, v167
	v_mov_b32_e32 v4, v167
	v_mov_b32_e32 v5, v167
	v_mov_b32_e32 v6, v167
	v_mov_b32_e32 v7, v167
	v_mov_b32_e32 v8, v167
	v_mov_b32_e32 v9, v167
	v_mov_b32_e32 v10, v167
	v_mov_b32_e32 v11, v167
	v_mov_b32_e32 v12, v167
	v_mov_b32_e32 v13, v167
	v_mov_b32_e32 v14, v167
	v_mov_b32_e32 v15, v167
	v_mov_b32_e32 v16, 0
	v_mov_b32_e32 v17, v167
	v_mov_b32_e32 v18, v167
	v_mov_b32_e32 v19, v167
	v_mov_b32_e32 v20, v167
	v_mov_b32_e32 v21, v167
	v_mov_b32_e32 v22, v167
	v_mov_b32_e32 v23, v167
	v_mov_b32_e32 v24, v167
	v_mov_b32_e32 v25, v167
	v_mov_b32_e32 v26, v167
	v_mov_b32_e32 v27, v167
	v_mov_b32_e32 v28, v167
	v_mov_b32_e32 v29, v167
	v_mov_b32_e32 v30, v167
	v_mov_b32_e32 v31, v167
	v_readfirstlane_b32 s98, v145
	s_nop 3
	s_lshr_b32 s98, s98, 8
	s_waitcnt lgkmcnt(0)
	s_barrier

; #define SBAR() __builtin_amdgcn_sched_barrier(0)
; __device__ __forceinline__ void attn_dense_body(const bf16* __restrict__ Qb, const bf16* __restrict__ Kh, const bf16* __restrict__ Vh,
;                                                 bf16* __restrict__ Ob, int seq, char* lds, const float negb) {
;     ...
;   for (int j = 1; j + 1 < NT; j += 2) {
;     SBAR(); qkt(pB0, pB1, (bf16*)((char*)K_lds + SHM_K), qr, r32, hi);
;     finishSM(pA0, pA1, negb, l_reg, pa0, pa1, pa2, pa3); SBAR();
.Lstg_2a:
	ds_read_b128 v[80:83], v198 offset:49152
	ds_read_b128 v[84:87], v198 offset:57344
	ds_read_b128 v[218:221], v199 offset:49152
	ds_read_b128 v[222:225], v199 offset:57344
	v_pk_add_f32 v[64:65], v[146:147], v[64:65]
	v_pk_add_f32 v[66:67], v[150:151], v[66:67]
	s_waitcnt lgkmcnt(3)
	v_mfma_f32_32x32x16_bf16 v[96:111], v[80:83], v[140:143], 0
	v_exp_f32_e32 v188, v64
	v_add_f32_e32 v64, 0, v214
	v_add_f32_e32 v64, v216, v64
	v_add_f32_e32 v64, v212, v64
	v_add_f32_e32 v64, v215, v64
	v_add_f32_e32 v64, v211, v64
	v_add_f32_e32 v64, v213, v64
	s_waitcnt lgkmcnt(2)
	v_mfma_f32_32x32x16_bf16 v[80:95], v[84:87], v[140:143], 0
	v_add_f32_e32 v64, v209, v64
	v_add_f32_e32 v64, v210, v64
	v_add_f32_e32 v64, v206, v64
	v_add_f32_e32 v64, v208, v64
	v_add_f32_e32 v64, v177, v64
	v_add_f32_e32 v64, v207, v64
	v_add_f32_e32 v64, v171, v64
	s_waitcnt lgkmcnt(1)
	v_mfma_f32_32x32x16_bf16 v[96:111], v[218:221], v[136:139], v[96:111]
	v_exp_f32_e32 v189, v65
	v_add_f32_e32 v64, v175, v64
	v_exp_f32_e32 v217, v66
	v_add_f32_e32 v64, v169, v64
	v_pk_add_f32 v[68:69], v[152:153], v[68:69]
	v_add_f32_e32 v64, v173, v64
	v_add_f32_e32 v64, v188, v64
	s_waitcnt lgkmcnt(0)
	v_mfma_f32_32x32x16_bf16 v[80:95], v[222:225], v[136:139], v[80:95]
	ds_read_b128 v[218:221], v200 offset:49152
	ds_read_b128 v[222:225], v200 offset:57344
	v_add_f32_e64 v70, v154, v70
	v_add_f32_e64 v71, v155, v71
	v_add_f32_e32 v64, v189, v64
	v_add_f32_e32 v64, v217, v64
	v_pk_add_f32 v[72:73], v[156:157], v[72:73]
	v_pk_add_f32 v[74:75], v[158:159], v[74:75]
	v_pk_add_f32 v[76:77], v[160:161], v[76:77]
	s_waitcnt lgkmcnt(1)
	v_mfma_f32_32x32x16_bf16 v[96:111], v[218:221], v[132:135], v[96:111]
	v_exp_f32_e32 v226, v75
	v_exp_f32_e32 v227, v76
	v_pk_add_f32 v[78:79], v[162:163], v[78:79]
	v_exp_f32_e32 v228, v77
	v_exp_f32_e32 v229, v78
	v_exp_f32_e32 v79, v79
	s_waitcnt lgkmcnt(0)
	v_mfma_f32_32x32x16_bf16 v[80:95], v[222:225], v[132:135], v[80:95]
	ds_read_b128 v[218:221], v201 offset:49152
	ds_read_b128 v[222:225], v201 offset:57344
	s_waitcnt lgkmcnt(1)
	v_mfma_f32_32x32x16_bf16 v[96:111], v[218:221], v[128:131], v[96:111]
	s_waitcnt lgkmcnt(0)
	v_mfma_f32_32x32x16_bf16 v[80:95], v[222:225], v[128:131], v[80:95]
	ds_read_b128 v[218:221], v202 offset:49152
	ds_read_b128 v[222:225], v202 offset:57344
	s_waitcnt lgkmcnt(1)
	v_mfma_f32_32x32x16_bf16 v[96:111], v[218:221], v[124:127], v[96:111]
	s_waitcnt lgkmcnt(0)
	v_mfma_f32_32x32x16_bf16 v[80:95], v[222:225], v[124:127], v[80:95]
	ds_read_b128 v[218:221], v203 offset:49152
	ds_read_b128 v[222:225], v203 offset:57344
	s_waitcnt lgkmcnt(1)
	v_mfma_f32_32x32x16_bf16 v[96:111], v[218:221], v[120:123], v[96:111]
	s_waitcnt lgkmcnt(0)
	v_mfma_f32_32x32x16_bf16 v[80:95], v[222:225], v[120:123], v[80:95]
	ds_read_b128 v[218:221], v204 offset:49152
	ds_read_b128 v[222:225], v204 offset:57344
	s_waitcnt lgkmcnt(1)
	v_mfma_f32_32x32x16_bf16 v[96:111], v[218:221], v[116:119], v[96:111]
	s_waitcnt lgkmcnt(0)
	v_mfma_f32_32x32x16_bf16 v[80:95], v[222:225], v[116:119], v[80:95]
	ds_read_b128 v[218:221], v205 offset:49152
	ds_read_b128 v[222:225], v205 offset:57344
	s_waitcnt lgkmcnt(1)
	v_mfma_f32_32x32x16_bf16 v[96:111], v[218:221], v[112:115], v[96:111]
	v_exp_f32_e32 v218, v67
	v_exp_f32_e32 v219, v68
	v_exp_f32_e32 v220, v69
	v_exp_f32_e32 v221, v70
	v_add_f32_e32 v64, v218, v64
	v_add_f32_e32 v64, v219, v64
	v_add_f32_e32 v64, v220, v64
	s_waitcnt lgkmcnt(0)
	v_mfma_f32_32x32x16_bf16 v[80:95], v[222:225], v[112:115], v[80:95]
	v_exp_f32_e32 v222, v71
	v_exp_f32_e32 v223, v72
	v_exp_f32_e32 v224, v73
	v_exp_f32_e32 v225, v74
	v_add_f32_e32 v64, v221, v64
	v_add_f32_e32 v64, v222, v64
	v_add_f32_e32 v64, v223, v64
	v_add_f32_e32 v64, v224, v64
	v_add_f32_e32 v64, v225, v64
	v_add_f32_e32 v64, v226, v64
	v_add_f32_e32 v64, v227, v64
	v_add_f32_e32 v64, v228, v64
	v_add_f32_e32 v64, v229, v64
	v_add_f32_e32 v64, v79, v64
	v_add_f32_e32 v167, v167, v64
	v_cvt_pk_bf16_f32 v64, v214, v216
	v_cvt_pk_bf16_f32 v65, v212, v215
	v_cvt_pk_bf16_f32 v66, v211, v213
	v_cvt_pk_bf16_f32 v67, v209, v210
	v_cvt_pk_bf16_f32 v68, v206, v208
	v_cvt_pk_bf16_f32 v69, v177, v207
	v_cvt_pk_bf16_f32 v70, v171, v175
	v_cvt_pk_bf16_f32 v71, v169, v173
	v_cvt_pk_bf16_f32 v72, v188, v189
	v_cvt_pk_bf16_f32 v73, v217, v218
	v_cvt_pk_bf16_f32 v74, v219, v220
	v_cvt_pk_bf16_f32 v75, v221, v222
	v_cvt_pk_bf16_f32 v76, v223, v224
	v_cvt_pk_bf16_f32 v77, v225, v226
	v_cvt_pk_bf16_f32 v78, v227, v228
	v_cvt_pk_bf16_f32 v79, v229, v79
	s_nop 0
	v_permlane32_swap_b32_e32 v64, v66
	v_permlane32_swap_b32_e32 v65, v67
	v_permlane32_swap_b32_e32 v68, v70
	v_permlane32_swap_b32_e32 v69, v71
	v_permlane32_swap_b32_e32 v72, v74
	v_permlane32_swap_b32_e32 v73, v75
	v_permlane32_swap_b32_e32 v76, v78
	v_permlane32_swap_b32_e32 v77, v79
	v_add_co_u32_e32 v210, vcc, s34, v178
	s_nop 1
	v_addc_co_u32_e32 v211, vcc, -1, v179, vcc
	global_load_dwordx4 v[206:209], v[210:211], off
	s_nop 0
	global_load_dwordx4 v[210:213], v[210:211], off offset:-512
	s_nop 0
	global_load_dwordx4 v[214:217], v[178:179], off
	global_load_dwordx4 v[218:221], v[178:179], off offset:-512
	ds_read_b64_tr_b16 v[222:223], v181 offset:0
	ds_read_b64_tr_b16 v[224:225], v181 offset:0x800
	ds_read_b64_tr_b16 v[226:227], v181 offset:0x1000
	ds_read_b64_tr_b16 v[228:229], v181 offset:0x1800
	ds_read_b64_tr_b16 v[230:231], v181 offset:0x2000
	ds_read_b64_tr_b16 v[232:233], v181 offset:0x2800
	ds_read_b64_tr_b16 v[234:235], v181 offset:0x3000
	ds_read_b64_tr_b16 v[236:237], v181 offset:0x3800
	s_waitcnt lgkmcnt(0)
; #define SBAR() __builtin_amdgcn_sched_barrier(0)
; __device__ __forceinline__ void expA(f32x16& p0, const float negb) { p0 = p0 + negb; for (int r = 0; r < 16; ++r) p0[r] = __builtin_amdgcn_exp2f(p0[r]); }
; #define SWRITE(b, i) do { *(bf16x8*)((char*)V_lds + (b) * SHM_V + vst0) = sr_[i].vs0;          \
;     *(bf16x8*)((char*)V_lds + (b) * SHM_V + vst1) = sr_[i].vs1; int kc = sc * 2;               \
;     *(bf16x8*)((char*)K_lds + (b) * SHM_K + KSWZ(sr, kc)) = sr_[i].ks0;                       \
;     *(bf16x8*)((char*)K_lds + (b) * SHM_K + KSWZ(32 + sr, kc)) = sr_[i].ks1; } while (0)
; #define SWAIT() asm volatile("s_waitcnt vmcnt(0)" ::: "memory")
; __device__ __forceinline__ void attn_dense_body(const bf16* __restrict__ Qb, const bf16* __restrict__ Kh, const bf16* __restrict__ Vh,
;                                                 bf16* __restrict__ Ob, int seq, char* lds, const float negb) {
;     ...
;     pv_d0(o, vb0, pa0, pa1, pa2, pa3); SBAR(); expA(pB0, negb); SBAR();
;     __syncthreads(); SWAIT(); SWRITE(0, SE); SBAR();
;     __syncthreads();
;     SBAR(); qkt(pA0, pA1, K_lds, qr, r32, hi);
;     finishSM(pB0, pB1, negb, l_reg, pa0, pa1, pa2, pa3); SBAR();
	s_nop 0
	v_mfma_f32_32x32x16_bf16 v[0:15], v[64:67], v[222:225], v[0:15]
	ds_read_b64_tr_b16 v[222:223], v181 offset:0x200
	ds_read_b64_tr_b16 v[224:225], v181 offset:0xa00
	v_mfma_f32_32x32x16_bf16 v[0:15], v[68:71], v[226:229], v[0:15]
	ds_read_b64_tr_b16 v[226:227], v181 offset:0x1200
	ds_read_b64_tr_b16 v[228:229], v181 offset:0x1a00
	v_mfma_f32_32x32x16_bf16 v[0:15], v[72:75], v[230:233], v[0:15]
	ds_read_b64_tr_b16 v[230:231], v181 offset:0x2200
	ds_read_b64_tr_b16 v[232:233], v181 offset:0x2a00
	ds_read_b64_tr_b16 v[238:239], v181 offset:0x3200
	ds_read_b64_tr_b16 v[240:241], v181 offset:0x3a00
	s_waitcnt lgkmcnt(0)
	v_mfma_f32_32x32x16_bf16 v[0:15], v[76:79], v[234:237], v[0:15]
	v_mfma_f32_32x32x16_bf16 v[16:31], v[64:67], v[222:225], v[16:31]
	ds_read_b64_tr_b16 v[222:223], v181 offset:0x400
	ds_read_b64_tr_b16 v[224:225], v181 offset:0xc00
	v_mfma_f32_32x32x16_bf16 v[16:31], v[68:71], v[226:229], v[16:31]
	ds_read_b64_tr_b16 v[226:227], v181 offset:0x1400
	ds_read_b64_tr_b16 v[228:229], v181 offset:0x1c00
	v_mfma_f32_32x32x16_bf16 v[16:31], v[72:75], v[230:233], v[16:31]
	ds_read_b64_tr_b16 v[230:231], v181 offset:0x2400
	ds_read_b64_tr_b16 v[232:233], v181 offset:0x2c00
	ds_read_b64_tr_b16 v[234:235], v181 offset:0x3400
	ds_read_b64_tr_b16 v[236:237], v181 offset:0x3c00
	s_waitcnt lgkmcnt(0)
	v_mfma_f32_32x32x16_bf16 v[16:31], v[76:79], v[238:241], v[16:31]
	v_mfma_f32_32x32x16_bf16 v[32:47], v[64:67], v[222:225], v[32:47]
	ds_read_b64_tr_b16 v[222:223], v181 offset:0x600
	ds_read_b64_tr_b16 v[224:225], v181 offset:0xe00
	v_mfma_f32_32x32x16_bf16 v[32:47], v[68:71], v[226:229], v[32:47]
	ds_read_b64_tr_b16 v[226:227], v181 offset:0x1600
	ds_read_b64_tr_b16 v[228:229], v181 offset:0x1e00
	v_mfma_f32_32x32x16_bf16 v[32:47], v[72:75], v[230:233], v[32:47]
	ds_read_b64_tr_b16 v[230:231], v181 offset:0x2600
	ds_read_b64_tr_b16 v[232:233], v181 offset:0x2e00
	ds_read_b64_tr_b16 v[238:239], v181 offset:0x3600
	ds_read_b64_tr_b16 v[240:241], v181 offset:0x3e00
	s_waitcnt lgkmcnt(0)
	v_mfma_f32_32x32x16_bf16 v[32:47], v[76:79], v[234:237], v[32:47]
	v_mfma_f32_32x32x16_bf16 v[48:63], v[64:67], v[222:225], v[48:63]
	v_mfma_f32_32x32x16_bf16 v[48:63], v[68:71], v[226:229], v[48:63]
	v_mfma_f32_32x32x16_bf16 v[48:63], v[72:75], v[230:233], v[48:63]
	v_mfma_f32_32x32x16_bf16 v[48:63], v[76:79], v[238:241], v[48:63]
	v_add_f32_e64 v74, v152, v100
	v_add_f32_e64 v75, v153, v101
	v_add_f32_e64 v76, v150, v98
	v_add_f32_e64 v77, v151, v99
	v_add_f32_e64 v78, v146, v96
	v_add_f32_e64 v79, v147, v97
	v_exp_f32_e32 v173, v76
	v_exp_f32_e32 v169, v78
	v_exp_f32_e32 v171, v79
	v_exp_f32_e32 v175, v77
	v_exp_f32_e32 v177, v74
	v_pk_add_f32 v[64:65], v[162:163], v[110:111]
	v_pk_add_f32 v[66:67], v[160:161], v[108:109]
	v_pk_add_f32 v[68:69], v[158:159], v[106:107]
	v_pk_add_f32 v[70:71], v[156:157], v[104:105]
	v_pk_add_f32 v[72:73], v[154:155], v[102:103]
	v_exp_f32_e32 v188, v75
	v_exp_f32_e32 v189, v72
	v_exp_f32_e32 v222, v73
	v_exp_f32_e32 v223, v70
	v_exp_f32_e32 v224, v71
	v_exp_f32_e32 v225, v68
	v_exp_f32_e32 v226, v69
	v_exp_f32_e32 v227, v66
	v_exp_f32_e32 v228, v67
	v_exp_f32_e32 v229, v64
	v_exp_f32_e32 v230, v65
	s_barrier
	s_waitcnt vmcnt(0)
	s_waitcnt vmcnt(3)
	ds_write_b128 v194, v[206:209]
	s_waitcnt vmcnt(1)
	ds_write_b128 v195, v[214:217]
	ds_write_b128 v196, v[210:213] offset:32768
	s_waitcnt vmcnt(0)
	ds_write_b128 v197, v[218:221] offset:32768
	s_waitcnt lgkmcnt(0)
	s_barrier
	s_cmp_eq_u32 s98, 0
	s_cbranch_scc1 .Lstg_2b
	s_sleep 2
.Lstg_2b:
	ds_read_b128 v[64:67], v198 offset:32768
	ds_read_b128 v[68:71], v198 offset:40960
	ds_read_b128 v[206:209], v199 offset:32768
	ds_read_b128 v[210:213], v199 offset:40960
	v_pk_add_f32 v[80:81], v[146:147], v[80:81]
	v_pk_add_f32 v[82:83], v[150:151], v[82:83]
	s_waitcnt lgkmcnt(3)
	v_mfma_f32_32x32x16_bf16 v[96:111], v[64:67], v[140:143], 0
	v_add_f32_e64 v84, v152, v84
	v_add_f32_e64 v85, v153, v85
	v_add_f32_e64 v86, v154, v86
	v_add_f32_e64 v87, v155, v87
	v_add_f32_e64 v88, v156, v88
	v_add_f32_e64 v89, v157, v89
	v_pk_add_f32 v[90:91], v[158:159], v[90:91]
	v_exp_f32_e32 v214, v88
	v_exp_f32_e32 v215, v89
	v_exp_f32_e32 v216, v90
	s_waitcnt lgkmcnt(2)
	v_mfma_f32_32x32x16_bf16 v[64:79], v[68:71], v[140:143], 0
	v_add_f32_e64 v92, v160, v92
	v_add_f32_e64 v93, v161, v93
	v_exp_f32_e32 v217, v91
	v_exp_f32_e32 v218, v92
	v_pk_add_f32 v[94:95], v[162:163], v[94:95]
	v_exp_f32_e32 v219, v93
	v_exp_f32_e32 v220, v94
	v_exp_f32_e32 v95, v95
	s_waitcnt lgkmcnt(1)
	v_mfma_f32_32x32x16_bf16 v[96:111], v[206:209], v[136:139], v[96:111]
	s_waitcnt lgkmcnt(0)
	v_mfma_f32_32x32x16_bf16 v[64:79], v[210:213], v[136:139], v[64:79]
	ds_read_b128 v[206:209], v200 offset:32768
	ds_read_b128 v[210:213], v200 offset:40960
	s_waitcnt lgkmcnt(1)
	v_mfma_f32_32x32x16_bf16 v[96:111], v[206:209], v[132:135], v[96:111]
	s_waitcnt lgkmcnt(0)
	v_mfma_f32_32x32x16_bf16 v[64:79], v[210:213], v[132:135], v[64:79]
	ds_read_b128 v[206:209], v201 offset:32768
	ds_read_b128 v[210:213], v201 offset:40960
	s_waitcnt lgkmcnt(1)
	v_mfma_f32_32x32x16_bf16 v[96:111], v[206:209], v[128:131], v[96:111]
	s_waitcnt lgkmcnt(0)
	v_mfma_f32_32x32x16_bf16 v[64:79], v[210:213], v[128:131], v[64:79]
	ds_read_b128 v[206:209], v202 offset:32768
	ds_read_b128 v[210:213], v202 offset:40960
	s_waitcnt lgkmcnt(1)
	v_mfma_f32_32x32x16_bf16 v[96:111], v[206:209], v[124:127], v[96:111]
	s_waitcnt lgkmcnt(0)
	v_mfma_f32_32x32x16_bf16 v[64:79], v[210:213], v[124:127], v[64:79]
	ds_read_b128 v[206:209], v203 offset:32768
	ds_read_b128 v[210:213], v203 offset:40960
	s_waitcnt lgkmcnt(1)
	v_mfma_f32_32x32x16_bf16 v[96:111], v[206:209], v[120:123], v[96:111]
	s_waitcnt lgkmcnt(0)
; #define SBAR() __builtin_amdgcn_sched_barrier(0)
; __device__ __forceinline__ void expA(f32x16& p0, const float negb) { p0 = p0 + negb; for (int r = 0; r < 16; ++r) p0[r] = __builtin_amdgcn_exp2f(p0[r]); }
; #define SLOAD(i, k0) do { const unsigned a_ = (unsigned)(k0) * (unsigned)LDK + so0; sr_[i].vs0 = ld8(Kh + (a_ + 256u)); sr_[i].vs1 = ld8(Kh + (a_ + 32u * LDK + 256u)); \
;     sr_[i].ks0 = ld8(Kh + a_); sr_[i].ks1 = ld8(Kh + (a_ + 32u * LDK)); } while (0)
; #define SWRITE(b, i) do { *(bf16x8*)((char*)V_lds + (b) * SHM_V + vst0) = sr_[i].vs0;          \
;     *(bf16x8*)((char*)V_lds + (b) * SHM_V + vst1) = sr_[i].vs1; int kc = sc * 2;               \
;     *(bf16x8*)((char*)K_lds + (b) * SHM_K + KSWZ(sr, kc)) = sr_[i].ks0;                       \
;     *(bf16x8*)((char*)K_lds + (b) * SHM_K + KSWZ(32 + sr, kc)) = sr_[i].ks1; } while (0)
; #define SWAIT() asm volatile("s_waitcnt vmcnt(0)" ::: "memory")
; __device__ __forceinline__ void attn_dense_body(const bf16* __restrict__ Qb, const bf16* __restrict__ Kh, const bf16* __restrict__ Vh,
;                                                 bf16* __restrict__ Ob, int seq, char* lds, const float negb) {
;     ...
;     finishSM(pB0, pB1, negb, l_reg, pa0, pa1, pa2, pa3); SBAR();
;     SLOAD(SE, (j + 2) * KVBLK); SBAR();
;     pv_d0(o, vb0 + (int)SHM_V, pa0, pa1, pa2, pa3); SBAR(); expA(pA0, negb); SBAR();
;     __syncthreads(); SWAIT(); SWRITE(1, SO); SBAR();
	v_mfma_f32_32x32x16_bf16 v[64:79], v[210:213], v[120:123], v[64:79]
	ds_read_b128 v[206:209], v204 offset:32768
	ds_read_b128 v[210:213], v204 offset:40960
	s_waitcnt lgkmcnt(1)
	v_mfma_f32_32x32x16_bf16 v[96:111], v[206:209], v[116:119], v[96:111]
	s_waitcnt lgkmcnt(0)
	v_mfma_f32_32x32x16_bf16 v[64:79], v[210:213], v[116:119], v[64:79]
	ds_read_b128 v[206:209], v205 offset:32768
	ds_read_b128 v[210:213], v205 offset:40960
	s_waitcnt lgkmcnt(1)
	v_mfma_f32_32x32x16_bf16 v[96:111], v[206:209], v[112:115], v[96:111]
	v_exp_f32_e32 v206, v80
	v_add_f32_e32 v80, 0, v169
	v_add_f32_e32 v80, v171, v80
	v_add_f32_e32 v80, v173, v80
	v_add_f32_e32 v80, v175, v80
	v_add_f32_e32 v80, v177, v80
	v_add_f32_e32 v80, v188, v80
	v_add_f32_e32 v80, v189, v80
	v_add_f32_e32 v80, v222, v80
	v_add_f32_e32 v80, v223, v80
	v_add_f32_e32 v80, v224, v80
	v_add_f32_e32 v80, v225, v80
	v_add_f32_e32 v80, v226, v80
	v_add_f32_e32 v80, v227, v80
	v_exp_f32_e32 v207, v81
	v_add_f32_e32 v80, v228, v80
	v_exp_f32_e32 v208, v82
	v_add_f32_e32 v80, v229, v80
	v_exp_f32_e32 v209, v83
	v_add_f32_e32 v80, v230, v80
	s_waitcnt lgkmcnt(0)
	v_mfma_f32_32x32x16_bf16 v[64:79], v[210:213], v[112:115], v[64:79]
	v_exp_f32_e32 v210, v84
	v_add_f32_e32 v80, v206, v80
	v_exp_f32_e32 v211, v85
	v_add_f32_e32 v80, v207, v80
	v_exp_f32_e32 v212, v86
	v_add_f32_e32 v80, v208, v80
	v_exp_f32_e32 v213, v87
	v_add_f32_e32 v80, v209, v80
	v_add_f32_e32 v80, v210, v80
	v_add_f32_e32 v80, v211, v80
	v_add_f32_e32 v80, v212, v80
	v_add_f32_e32 v80, v213, v80
	v_add_f32_e32 v80, v214, v80
	v_add_f32_e32 v80, v215, v80
	v_add_f32_e32 v80, v216, v80
	v_add_f32_e32 v80, v217, v80
	v_add_f32_e32 v80, v218, v80
	v_add_f32_e32 v80, v219, v80
	v_add_f32_e32 v80, v220, v80
	v_add_f32_e32 v80, v95, v80
	v_add_f32_e32 v167, v167, v80
	v_cvt_pk_bf16_f32 v80, v169, v171
	v_cvt_pk_bf16_f32 v81, v173, v175
	v_cvt_pk_bf16_f32 v82, v177, v188
	v_cvt_pk_bf16_f32 v83, v189, v222
	v_cvt_pk_bf16_f32 v84, v223, v224
	v_cvt_pk_bf16_f32 v85, v225, v226
	v_cvt_pk_bf16_f32 v86, v227, v228
	v_cvt_pk_bf16_f32 v87, v229, v230
	v_cvt_pk_bf16_f32 v88, v206, v207
	v_cvt_pk_bf16_f32 v89, v208, v209
	v_cvt_pk_bf16_f32 v90, v210, v211
	v_cvt_pk_bf16_f32 v91, v212, v213
	v_cvt_pk_bf16_f32 v92, v214, v215
	v_cvt_pk_bf16_f32 v93, v216, v217
	v_cvt_pk_bf16_f32 v94, v218, v219
	v_cvt_pk_bf16_f32 v95, v220, v95
	s_nop 0
	v_permlane32_swap_b32_e32 v80, v82
	v_permlane32_swap_b32_e32 v81, v83
	v_permlane32_swap_b32_e32 v84, v86
	v_permlane32_swap_b32_e32 v85, v87
	v_permlane32_swap_b32_e32 v88, v90
	v_permlane32_swap_b32_e32 v89, v91
	v_permlane32_swap_b32_e32 v92, v94
	v_permlane32_swap_b32_e32 v93, v95
	v_add_u32_e32 v210, 0xc100, v148
	v_mov_b32_e32 v211, v149
	v_lshl_add_u64 v[206:207], v[148:149], 1, s[60:61]
	v_add_u32_e32 v208, 0xc000, v148
	v_lshl_add_u64 v[210:211], v[210:211], 1, s[62:63]
	v_mov_b32_e32 v209, v149
	global_load_dwordx4 v[218:221], v[206:207], off offset:2560
	global_load_dwordx4 v[222:225], v[206:207], off offset:2048
	v_lshl_add_u64 v[206:207], v[208:209], 1, s[62:63]
	global_load_dwordx4 v[226:229], v[210:211], off
	global_load_dwordx4 v[230:233], v[206:207], off
	ds_read_b64_tr_b16 v[206:207], v191 offset:0
	ds_read_b64_tr_b16 v[208:209], v191 offset:0x800
	ds_read_b64_tr_b16 v[210:211], v191 offset:0x1000
	ds_read_b64_tr_b16 v[212:213], v191 offset:0x1800
	ds_read_b64_tr_b16 v[214:215], v191 offset:0x2000
	ds_read_b64_tr_b16 v[216:217], v191 offset:0x2800
	ds_read_b64_tr_b16 v[234:235], v191 offset:0x3000
	ds_read_b64_tr_b16 v[236:237], v191 offset:0x3800
	s_waitcnt lgkmcnt(0)
	s_nop 0
	v_mfma_f32_32x32x16_bf16 v[0:15], v[80:83], v[206:209], v[0:15]
	ds_read_b64_tr_b16 v[206:207], v191 offset:0x200
	ds_read_b64_tr_b16 v[208:209], v191 offset:0xa00
	v_mfma_f32_32x32x16_bf16 v[0:15], v[84:87], v[210:213], v[0:15]
	ds_read_b64_tr_b16 v[210:211], v191 offset:0x1200
	ds_read_b64_tr_b16 v[212:213], v191 offset:0x1a00
	v_mfma_f32_32x32x16_bf16 v[0:15], v[88:91], v[214:217], v[0:15]
	ds_read_b64_tr_b16 v[214:215], v191 offset:0x2200
	ds_read_b64_tr_b16 v[216:217], v191 offset:0x2a00
	ds_read_b64_tr_b16 v[238:239], v191 offset:0x3200
	ds_read_b64_tr_b16 v[240:241], v191 offset:0x3a00
	s_waitcnt lgkmcnt(0)
	v_mfma_f32_32x32x16_bf16 v[0:15], v[92:95], v[234:237], v[0:15]
	v_mfma_f32_32x32x16_bf16 v[16:31], v[80:83], v[206:209], v[16:31]
	ds_read_b64_tr_b16 v[206:207], v191 offset:0x400
	ds_read_b64_tr_b16 v[208:209], v191 offset:0xc00
	v_mfma_f32_32x32x16_bf16 v[16:31], v[84:87], v[210:213], v[16:31]
	ds_read_b64_tr_b16 v[210:211], v191 offset:0x1400
	ds_read_b64_tr_b16 v[212:213], v191 offset:0x1c00
	v_mfma_f32_32x32x16_bf16 v[16:31], v[88:91], v[214:217], v[16:31]
	ds_read_b64_tr_b16 v[214:215], v191 offset:0x2400
	ds_read_b64_tr_b16 v[216:217], v191 offset:0x2c00
	ds_read_b64_tr_b16 v[234:235], v191 offset:0x3400
	ds_read_b64_tr_b16 v[236:237], v191 offset:0x3c00
	s_waitcnt lgkmcnt(0)
	v_mfma_f32_32x32x16_bf16 v[16:31], v[92:95], v[238:241], v[16:31]
	v_mfma_f32_32x32x16_bf16 v[32:47], v[80:83], v[206:209], v[32:47]
	ds_read_b64_tr_b16 v[206:207], v191 offset:0x600
	ds_read_b64_tr_b16 v[208:209], v191 offset:0xe00
	v_mfma_f32_32x32x16_bf16 v[32:47], v[84:87], v[210:213], v[32:47]
	ds_read_b64_tr_b16 v[210:211], v191 offset:0x1600
	ds_read_b64_tr_b16 v[212:213], v191 offset:0x1e00
	v_mfma_f32_32x32x16_bf16 v[32:47], v[88:91], v[214:217], v[32:47]
	ds_read_b64_tr_b16 v[214:215], v191 offset:0x2600
	ds_read_b64_tr_b16 v[216:217], v191 offset:0x2e00
	ds_read_b64_tr_b16 v[238:239], v191 offset:0x3600
	ds_read_b64_tr_b16 v[240:241], v191 offset:0x3e00
	s_waitcnt lgkmcnt(0)
	v_mfma_f32_32x32x16_bf16 v[32:47], v[92:95], v[234:237], v[32:47]
	v_mfma_f32_32x32x16_bf16 v[48:63], v[80:83], v[206:209], v[48:63]
	v_mfma_f32_32x32x16_bf16 v[48:63], v[84:87], v[210:213], v[48:63]
	v_mfma_f32_32x32x16_bf16 v[48:63], v[88:91], v[214:217], v[48:63]
	v_mfma_f32_32x32x16_bf16 v[48:63], v[92:95], v[238:241], v[48:63]
	v_add_f32_e64 v80, v162, v110
	v_add_f32_e64 v81, v163, v111
	v_add_f32_e64 v82, v160, v108
	v_add_f32_e64 v83, v161, v109
	v_add_f32_e64 v84, v158, v106
	v_add_f32_e64 v85, v159, v107
	v_pk_add_f32 v[86:87], v[156:157], v[104:105]
	v_pk_add_f32 v[88:89], v[154:155], v[102:103]
	v_pk_add_f32 v[90:91], v[152:153], v[100:101]
	v_pk_add_f32 v[92:93], v[150:151], v[98:99]
	v_pk_add_f32 v[94:95], v[146:147], v[96:97]
	v_exp_f32_e32 v212, v92
	v_exp_f32_e32 v214, v94
	v_exp_f32_e32 v216, v95
	v_exp_f32_e32 v215, v93
	v_exp_f32_e32 v211, v90
	v_exp_f32_e32 v213, v91
	v_exp_f32_e32 v209, v88
	v_exp_f32_e32 v210, v89
	v_exp_f32_e32 v206, v86
	v_exp_f32_e32 v208, v87
	v_exp_f32_e32 v177, v84
	v_exp_f32_e32 v207, v85
	v_exp_f32_e32 v171, v82
	v_exp_f32_e32 v175, v83
	v_exp_f32_e32 v169, v80
	v_exp_f32_e32 v173, v81
	s_barrier
; #define SBAR() __builtin_amdgcn_sched_barrier(0)
; #define SWRITE(b, i) do { *(bf16x8*)((char*)V_lds + (b) * SHM_V + vst0) = sr_[i].vs0;          \
;     *(bf16x8*)((char*)V_lds + (b) * SHM_V + vst1) = sr_[i].vs1; int kc = sc * 2;               \
;     *(bf16x8*)((char*)K_lds + (b) * SHM_K + KSWZ(sr, kc)) = sr_[i].ks0;                       \
;     *(bf16x8*)((char*)K_lds + (b) * SHM_K + KSWZ(32 + sr, kc)) = sr_[i].ks1; } while (0)
; #define SWAIT() asm volatile("s_waitcnt vmcnt(0)" ::: "memory")
; __device__ __forceinline__ void attn_dense_body(const bf16* __restrict__ Qb, const bf16* __restrict__ Kh, const bf16* __restrict__ Vh,
;                                                 bf16* __restrict__ Ob, int seq, char* lds, const float negb) {
;     ...
;     __syncthreads(); SWAIT(); SWRITE(1, SO); SBAR();
;     __syncthreads();
;   }
;   SBAR(); qkt(pB0, pB1, (bf16*)((char*)K_lds + SHM_K), qr, r32, hi);
;   finishSM(pA0, pA1, negb, l_reg, pa0, pa1, pa2, pa3); SBAR();
	s_waitcnt vmcnt(0)
	s_waitcnt vmcnt(3)
	ds_write_b128 v194, v[218:221] offset:16384
	s_waitcnt vmcnt(1)
	ds_write_b128 v195, v[226:229] offset:16384
	ds_write_b128 v196, v[222:225] offset:49152
	s_waitcnt vmcnt(0)
	ds_write_b128 v197, v[230:233] offset:49152
	s_add_i32 s64, s64, 2
	v_add_u32_e32 v148, 0x30000, v148
	s_cmp_ge_u32 s64, s82
	v_lshl_add_u64 v[178:179], v[178:179], 0, s[6:7]
	s_waitcnt lgkmcnt(0)
	s_barrier
	s_cbranch_scc0 .LBB0_516
	ds_read_b128 v[80:83], v198 offset:49152
	ds_read_b128 v[84:87], v198 offset:57344
	v_pk_add_f32 v[64:65], v[146:147], v[64:65]
	v_pk_add_f32 v[66:67], v[150:151], v[66:67]
	v_pk_add_f32 v[68:69], v[152:153], v[68:69]
	s_waitcnt lgkmcnt(1)
	v_mfma_f32_32x32x16_bf16 v[96:111], v[80:83], v[140:143], 0
	v_add_f32_e64 v70, v154, v70
	v_add_f32_e64 v71, v155, v71
	v_add_f32_e64 v72, v156, v72
	v_add_f32_e64 v73, v157, v73
	v_add_f32_e64 v74, v158, v74
	v_add_f32_e64 v75, v159, v75
	v_pk_add_f32 v[76:77], v[160:161], v[76:77]
	v_pk_add_f32 v[78:79], v[162:163], v[78:79]
	s_nop 0
	v_exp_f32_e32 v79, v79
	s_waitcnt lgkmcnt(0)
	v_mfma_f32_32x32x16_bf16 v[80:95], v[84:87], v[140:143], 0
	ds_read_b128 v[140:143], v199 offset:49152
	ds_read_b128 v[218:221], v199 offset:57344
	s_waitcnt lgkmcnt(1)
	v_mfma_f32_32x32x16_bf16 v[96:111], v[140:143], v[136:139], v[96:111]
	s_waitcnt lgkmcnt(0)
	v_mfma_f32_32x32x16_bf16 v[80:95], v[218:221], v[136:139], v[80:95]
	ds_read_b128 v[136:139], v200 offset:49152
	ds_read_b128 v[140:143], v200 offset:57344
	s_waitcnt lgkmcnt(1)
	v_mfma_f32_32x32x16_bf16 v[96:111], v[136:139], v[132:135], v[96:111]
	s_waitcnt lgkmcnt(0)
	v_mfma_f32_32x32x16_bf16 v[80:95], v[140:143], v[132:135], v[80:95]
	ds_read_b128 v[132:135], v201 offset:49152
	ds_read_b128 v[136:139], v201 offset:57344
	s_waitcnt lgkmcnt(1)
	v_mfma_f32_32x32x16_bf16 v[96:111], v[132:135], v[128:131], v[96:111]
	s_waitcnt lgkmcnt(0)
	v_mfma_f32_32x32x16_bf16 v[80:95], v[136:139], v[128:131], v[80:95]
	ds_read_b128 v[128:131], v202 offset:49152
	ds_read_b128 v[132:135], v202 offset:57344
	s_waitcnt lgkmcnt(1)
	v_mfma_f32_32x32x16_bf16 v[96:111], v[128:131], v[124:127], v[96:111]
	s_waitcnt lgkmcnt(0)
	v_mfma_f32_32x32x16_bf16 v[80:95], v[132:135], v[124:127], v[80:95]
	ds_read_b128 v[124:127], v203 offset:49152
	ds_read_b128 v[128:131], v203 offset:57344
	s_waitcnt lgkmcnt(1)
	v_mfma_f32_32x32x16_bf16 v[96:111], v[124:127], v[120:123], v[96:111]
	s_waitcnt lgkmcnt(0)
	v_mfma_f32_32x32x16_bf16 v[80:95], v[128:131], v[120:123], v[80:95]
	ds_read_b128 v[120:123], v204 offset:49152
	ds_read_b128 v[124:127], v204 offset:57344
	s_waitcnt lgkmcnt(1)
	v_mfma_f32_32x32x16_bf16 v[96:111], v[120:123], v[116:119], v[96:111]
	s_waitcnt lgkmcnt(0)
	v_mfma_f32_32x32x16_bf16 v[80:95], v[124:127], v[116:119], v[80:95]
	ds_read_b128 v[116:119], v205 offset:49152
	ds_read_b128 v[120:123], v205 offset:57344
	v_exp_f32_e32 v124, v76
	v_exp_f32_e32 v125, v77
	v_exp_f32_e32 v126, v78
	s_waitcnt lgkmcnt(1)
	v_mfma_f32_32x32x16_bf16 v[96:111], v[116:119], v[112:115], v[96:111]
	v_exp_f32_e32 v116, v68
	v_exp_f32_e32 v117, v69
	v_exp_f32_e32 v118, v70
	v_exp_f32_e32 v119, v71
	s_waitcnt lgkmcnt(0)
	v_mfma_f32_32x32x16_bf16 v[80:95], v[120:123], v[112:115], v[80:95]
	v_exp_f32_e32 v112, v64
	v_add_f32_e32 v64, 0, v214
	v_add_f32_e32 v64, v216, v64
	v_add_f32_e32 v64, v212, v64
	v_add_f32_e32 v64, v215, v64
	v_add_f32_e32 v64, v211, v64
	v_add_f32_e32 v64, v213, v64
	v_add_f32_e32 v64, v209, v64
	v_add_f32_e32 v64, v210, v64
	v_add_f32_e32 v64, v206, v64
	v_add_f32_e32 v64, v208, v64
	v_add_f32_e32 v64, v177, v64
	v_add_f32_e32 v64, v207, v64
	v_add_f32_e32 v64, v171, v64
	v_exp_f32_e32 v113, v65
	v_add_f32_e32 v64, v175, v64
	v_exp_f32_e32 v114, v66
	v_add_f32_e32 v64, v169, v64
	v_exp_f32_e32 v115, v67
	v_add_f32_e32 v64, v173, v64
	v_add_f32_e32 v64, v112, v64
	v_add_f32_e32 v64, v113, v64
	v_add_f32_e32 v64, v114, v64
	v_add_f32_e32 v64, v115, v64
	v_exp_f32_e32 v120, v72
	v_add_f32_e32 v64, v116, v64
	v_exp_f32_e32 v121, v73
	v_add_f32_e32 v64, v117, v64
	v_exp_f32_e32 v122, v74
	v_add_f32_e32 v64, v118, v64
	v_exp_f32_e32 v123, v75
	v_add_f32_e32 v64, v119, v64
	v_add_f32_e32 v64, v120, v64
	v_add_f32_e32 v64, v121, v64
	v_add_f32_e32 v64, v122, v64
	v_add_f32_e32 v64, v123, v64
	v_add_f32_e32 v64, v124, v64
	v_add_f32_e32 v64, v125, v64
	v_add_f32_e32 v64, v126, v64
	v_add_f32_e32 v64, v79, v64
	v_add_f32_e32 v132, v167, v64
	v_cvt_pk_bf16_f32 v64, v214, v216
	v_cvt_pk_bf16_f32 v65, v212, v215
	v_cvt_pk_bf16_f32 v66, v211, v213
	v_cvt_pk_bf16_f32 v67, v209, v210
	v_cvt_pk_bf16_f32 v68, v206, v208
	v_cvt_pk_bf16_f32 v69, v177, v207
	v_cvt_pk_bf16_f32 v70, v171, v175
	v_cvt_pk_bf16_f32 v71, v169, v173
	s_nop 0
	v_permlane32_swap_b32_e32 v64, v66
	v_permlane32_swap_b32_e32 v65, v67
	v_cvt_pk_bf16_f32 v72, v112, v113
	v_cvt_pk_bf16_f32 v73, v114, v115
	v_cvt_pk_bf16_f32 v74, v116, v117
	v_cvt_pk_bf16_f32 v75, v118, v119
	v_cvt_pk_bf16_f32 v76, v120, v121
	v_cvt_pk_bf16_f32 v77, v122, v123
	v_cvt_pk_bf16_f32 v78, v124, v125
	v_cvt_pk_bf16_f32 v79, v126, v79
	v_permlane32_swap_b32_e32 v68, v70
	v_permlane32_swap_b32_e32 v69, v71
	v_permlane32_swap_b32_e32 v72, v74
	v_permlane32_swap_b32_e32 v73, v75
	v_permlane32_swap_b32_e32 v76, v78
	v_permlane32_swap_b32_e32 v77, v79
	ds_read_b64_tr_b16 v[112:113], v181 offset:0
	ds_read_b64_tr_b16 v[114:115], v181 offset:0x800
	ds_read_b64_tr_b16 v[116:117], v181 offset:0x1000
	ds_read_b64_tr_b16 v[118:119], v181 offset:0x1800
	ds_read_b64_tr_b16 v[120:121], v181 offset:0x2000
	ds_read_b64_tr_b16 v[122:123], v181 offset:0x2800
	ds_read_b64_tr_b16 v[124:125], v181 offset:0x3000
	ds_read_b64_tr_b16 v[126:127], v181 offset:0x3800
	s_waitcnt lgkmcnt(0)
; #define SBAR() __builtin_amdgcn_sched_barrier(0)
; __device__ __forceinline__ void expA(f32x16& p0, const float negb) { p0 = p0 + negb; for (int r = 0; r < 16; ++r) p0[r] = __builtin_amdgcn_exp2f(p0[r]); }
; __device__ __forceinline__ void attn_dense_body(const bf16* __restrict__ Qb, const bf16* __restrict__ Kh, const bf16* __restrict__ Vh,
;                                                 bf16* __restrict__ Ob, int seq, char* lds, const float negb) {
;     ...
;   finishSM(pA0, pA1, negb, l_reg, pa0, pa1, pa2, pa3); SBAR();
;   pv_d0(o, vb0, pa0, pa1, pa2, pa3); expA(pB0, negb);
;   __syncthreads();
;   finishSM(pB0, pB1, negb, l_reg, pa0, pa1, pa2, pa3); SBAR();
	s_nop 0
	v_mfma_f32_32x32x16_bf16 v[0:15], v[64:67], v[112:115], v[0:15]
	ds_read_b64_tr_b16 v[112:113], v181 offset:0x200
	ds_read_b64_tr_b16 v[114:115], v181 offset:0xa00
	v_mfma_f32_32x32x16_bf16 v[0:15], v[68:71], v[116:119], v[0:15]
	ds_read_b64_tr_b16 v[116:117], v181 offset:0x1200
	ds_read_b64_tr_b16 v[118:119], v181 offset:0x1a00
	v_mfma_f32_32x32x16_bf16 v[0:15], v[72:75], v[120:123], v[0:15]
	ds_read_b64_tr_b16 v[120:121], v181 offset:0x2200
	ds_read_b64_tr_b16 v[122:123], v181 offset:0x2a00
	ds_read_b64_tr_b16 v[128:129], v181 offset:0x3200
	ds_read_b64_tr_b16 v[130:131], v181 offset:0x3a00
	s_waitcnt lgkmcnt(0)
	v_mfma_f32_32x32x16_bf16 v[0:15], v[76:79], v[124:127], v[0:15]
	v_mfma_f32_32x32x16_bf16 v[16:31], v[64:67], v[112:115], v[16:31]
	ds_read_b64_tr_b16 v[112:113], v181 offset:0x400
	ds_read_b64_tr_b16 v[114:115], v181 offset:0xc00
	v_mfma_f32_32x32x16_bf16 v[16:31], v[68:71], v[116:119], v[16:31]
	ds_read_b64_tr_b16 v[116:117], v181 offset:0x1400
	ds_read_b64_tr_b16 v[118:119], v181 offset:0x1c00
	v_mfma_f32_32x32x16_bf16 v[16:31], v[72:75], v[120:123], v[16:31]
	ds_read_b64_tr_b16 v[120:121], v181 offset:0x2400
	ds_read_b64_tr_b16 v[122:123], v181 offset:0x2c00
	ds_read_b64_tr_b16 v[124:125], v181 offset:0x3400
	ds_read_b64_tr_b16 v[126:127], v181 offset:0x3c00
	s_waitcnt lgkmcnt(0)
	v_mfma_f32_32x32x16_bf16 v[16:31], v[76:79], v[128:131], v[16:31]
	v_mfma_f32_32x32x16_bf16 v[32:47], v[64:67], v[112:115], v[32:47]
	ds_read_b64_tr_b16 v[112:113], v181 offset:0x600
	ds_read_b64_tr_b16 v[114:115], v181 offset:0xe00
	v_mfma_f32_32x32x16_bf16 v[32:47], v[68:71], v[116:119], v[32:47]
	ds_read_b64_tr_b16 v[116:117], v181 offset:0x1600
	ds_read_b64_tr_b16 v[118:119], v181 offset:0x1e00
	v_mfma_f32_32x32x16_bf16 v[32:47], v[72:75], v[120:123], v[32:47]
	ds_read_b64_tr_b16 v[120:121], v181 offset:0x2600
	ds_read_b64_tr_b16 v[122:123], v181 offset:0x2e00
	ds_read_b64_tr_b16 v[128:129], v181 offset:0x3600
	ds_read_b64_tr_b16 v[130:131], v181 offset:0x3e00
	s_waitcnt lgkmcnt(0)
	v_mfma_f32_32x32x16_bf16 v[32:47], v[76:79], v[124:127], v[32:47]
	v_mfma_f32_32x32x16_bf16 v[48:63], v[64:67], v[112:115], v[48:63]
	v_add_f32_e64 v66, v146, v96
	v_add_f32_e64 v67, v147, v97
	v_add_f32_e64 v64, v150, v98
	v_add_f32_e64 v65, v151, v99
	v_exp_f32_e32 v96, v66
	v_exp_f32_e32 v97, v67
	v_exp_f32_e32 v98, v64
	v_pk_add_f32 v[100:101], v[152:153], v[100:101]
	v_exp_f32_e32 v99, v65
	v_mfma_f32_32x32x16_bf16 v[48:63], v[68:71], v[116:119], v[48:63]
	v_add_f32_e64 v64, v162, v94
	v_add_f32_e64 v65, v163, v95
	v_exp_f32_e32 v100, v100
	v_pk_add_f32 v[68:69], v[158:159], v[90:91]
	v_exp_f32_e32 v90, v64
	v_add_f32_e32 v64, 0, v96
	v_pk_add_f32 v[102:103], v[154:155], v[102:103]
	v_exp_f32_e32 v101, v101
	v_add_f32_e32 v64, v97, v64
	v_exp_f32_e32 v102, v102
	v_add_f32_e32 v64, v98, v64
	v_pk_add_f32 v[104:105], v[156:157], v[104:105]
	v_exp_f32_e32 v103, v103
	v_mfma_f32_32x32x16_bf16 v[48:63], v[72:75], v[120:123], v[48:63]
	v_add_f32_e32 v64, v99, v64
	v_exp_f32_e32 v104, v104
	v_add_f32_e32 v64, v100, v64
	v_pk_add_f32 v[106:107], v[158:159], v[106:107]
	v_exp_f32_e32 v105, v105
	v_add_f32_e32 v64, v101, v64
	v_exp_f32_e32 v106, v106
	v_add_f32_e32 v64, v102, v64
	v_pk_add_f32 v[108:109], v[160:161], v[108:109]
	v_exp_f32_e32 v107, v107
	v_add_f32_e32 v64, v103, v64
	v_exp_f32_e32 v108, v108
	v_add_f32_e32 v64, v104, v64
	v_pk_add_f32 v[110:111], v[162:163], v[110:111]
	v_exp_f32_e32 v109, v109
	v_add_f32_e32 v64, v105, v64
	v_exp_f32_e32 v110, v110
	v_add_f32_e32 v64, v106, v64
	v_exp_f32_e32 v111, v111
	v_mfma_f32_32x32x16_bf16 v[48:63], v[76:79], v[128:131], v[48:63]
	v_add_f32_e64 v78, v146, v80
	v_add_f32_e64 v79, v147, v81
	v_add_f32_e32 v64, v107, v64
	v_exp_f32_e32 v78, v78
	v_add_f32_e32 v64, v108, v64
	v_pk_add_f32 v[76:77], v[150:151], v[82:83]
	v_exp_f32_e32 v79, v79
	v_add_f32_e32 v64, v109, v64
	v_exp_f32_e32 v76, v76
	v_add_f32_e32 v64, v110, v64
	v_pk_add_f32 v[74:75], v[152:153], v[84:85]
	v_exp_f32_e32 v77, v77
	v_add_f32_e32 v64, v111, v64
	v_exp_f32_e32 v80, v74
	v_add_f32_e32 v64, v78, v64
	v_pk_add_f32 v[72:73], v[154:155], v[86:87]
	v_exp_f32_e32 v81, v75
	v_add_f32_e32 v64, v79, v64
	v_exp_f32_e32 v82, v72
	v_add_f32_e32 v64, v76, v64
	v_pk_add_f32 v[70:71], v[156:157], v[88:89]
	v_exp_f32_e32 v83, v73
	v_add_f32_e32 v64, v77, v64
	v_exp_f32_e32 v84, v70
	v_add_f32_e32 v64, v80, v64
	v_exp_f32_e32 v85, v71
	v_add_f32_e32 v64, v81, v64
	v_exp_f32_e32 v86, v68
	v_add_f32_e32 v64, v82, v64
	v_pk_add_f32 v[66:67], v[160:161], v[92:93]
	v_exp_f32_e32 v87, v69
	v_add_f32_e32 v64, v83, v64
	v_exp_f32_e32 v88, v66
	v_add_f32_e32 v64, v84, v64
	v_exp_f32_e32 v89, v67
	v_add_f32_e32 v64, v85, v64
	v_add_f32_e32 v64, v86, v64
	v_exp_f32_e32 v65, v65
	v_add_f32_e32 v64, v87, v64
	v_add_f32_e32 v64, v88, v64
	v_add_f32_e32 v64, v89, v64
	v_add_f32_e32 v64, v90, v64
	v_add_f32_e32 v64, v65, v64
	s_barrier
; #define SBAR() __builtin_amdgcn_sched_barrier(0)
; __device__ __forceinline__ void attn_dense_body(const bf16* __restrict__ Qb, const bf16* __restrict__ Kh, const bf16* __restrict__ Vh,
;                                                 bf16* __restrict__ Ob, int seq, char* lds, const float negb) {
;     ...
;   finishSM(pB0, pB1, negb, l_reg, pa0, pa1, pa2, pa3); SBAR();
;   pv_d0(o, vb0 + (int)SHM_V, pa0, pa1, pa2, pa3);
;   { auto rr = __builtin_amdgcn_permlane32_swap(__float_as_uint(l_reg), __float_as_uint(l_reg), false, false); l_reg = __uint_as_float(rr[0]) + __uint_as_float(rr[1]); }
;   if (hi == 0) li_l[r32] = l_reg; asm volatile("s_waitcnt lgkmcnt(0)" ::: "memory");
	v_add_f32_e32 v64, v132, v64
	v_cvt_pk_bf16_f32 v66, v96, v97
	v_cvt_pk_bf16_f32 v67, v98, v99
	v_cvt_pk_bf16_f32 v68, v100, v101
	v_cvt_pk_bf16_f32 v69, v102, v103
	v_cvt_pk_bf16_f32 v70, v104, v105
	v_cvt_pk_bf16_f32 v71, v106, v107
	v_cvt_pk_bf16_f32 v72, v108, v109
	v_cvt_pk_bf16_f32 v73, v110, v111
	v_cvt_pk_bf16_f32 v74, v78, v79
	v_cvt_pk_bf16_f32 v75, v76, v77
	v_cvt_pk_bf16_f32 v76, v80, v81
	v_cvt_pk_bf16_f32 v77, v82, v83
	v_cvt_pk_bf16_f32 v78, v84, v85
	v_cvt_pk_bf16_f32 v79, v86, v87
	v_cvt_pk_bf16_f32 v80, v88, v89
	v_cvt_pk_bf16_f32 v81, v90, v65
	s_nop 0
	v_permlane32_swap_b32_e32 v66, v68
	v_permlane32_swap_b32_e32 v67, v69
	v_permlane32_swap_b32_e32 v70, v72
	v_permlane32_swap_b32_e32 v71, v73
	v_permlane32_swap_b32_e32 v74, v76
	v_permlane32_swap_b32_e32 v75, v77
	v_permlane32_swap_b32_e32 v78, v80
	v_permlane32_swap_b32_e32 v79, v81
	ds_read_b64_tr_b16 v[82:83], v191 offset:0
	ds_read_b64_tr_b16 v[84:85], v191 offset:0x800
	ds_read_b64_tr_b16 v[86:87], v191 offset:0x1000
	ds_read_b64_tr_b16 v[88:89], v191 offset:0x1800
	ds_read_b64_tr_b16 v[90:91], v191 offset:0x2000
	ds_read_b64_tr_b16 v[92:93], v191 offset:0x2800
	ds_read_b64_tr_b16 v[94:95], v191 offset:0x3000
	ds_read_b64_tr_b16 v[96:97], v191 offset:0x3800
	s_waitcnt lgkmcnt(0)
	s_nop 0
	v_mfma_f32_32x32x16_bf16 v[0:15], v[66:69], v[82:85], v[0:15]
	ds_read_b64_tr_b16 v[82:83], v191 offset:0x200
	ds_read_b64_tr_b16 v[84:85], v191 offset:0xa00
	v_mfma_f32_32x32x16_bf16 v[0:15], v[70:73], v[86:89], v[0:15]
	ds_read_b64_tr_b16 v[86:87], v191 offset:0x1200
	ds_read_b64_tr_b16 v[88:89], v191 offset:0x1a00
	v_mfma_f32_32x32x16_bf16 v[0:15], v[74:77], v[90:93], v[0:15]
	ds_read_b64_tr_b16 v[90:91], v191 offset:0x2200
	ds_read_b64_tr_b16 v[92:93], v191 offset:0x2a00
	ds_read_b64_tr_b16 v[98:99], v191 offset:0x3200
	ds_read_b64_tr_b16 v[100:101], v191 offset:0x3a00
	s_waitcnt lgkmcnt(0)
	v_mfma_f32_32x32x16_bf16 v[0:15], v[78:81], v[94:97], v[0:15]
	v_mfma_f32_32x32x16_bf16 v[16:31], v[66:69], v[82:85], v[16:31]
	ds_read_b64_tr_b16 v[82:83], v191 offset:0x400
	ds_read_b64_tr_b16 v[84:85], v191 offset:0xc00
	v_mfma_f32_32x32x16_bf16 v[16:31], v[70:73], v[86:89], v[16:31]
	ds_read_b64_tr_b16 v[86:87], v191 offset:0x1400
	ds_read_b64_tr_b16 v[88:89], v191 offset:0x1c00
	v_mfma_f32_32x32x16_bf16 v[16:31], v[74:77], v[90:93], v[16:31]
	ds_read_b64_tr_b16 v[90:91], v191 offset:0x2400
	ds_read_b64_tr_b16 v[92:93], v191 offset:0x2c00
	ds_read_b64_tr_b16 v[94:95], v191 offset:0x3400
	ds_read_b64_tr_b16 v[96:97], v191 offset:0x3c00
	s_waitcnt lgkmcnt(0)
	v_mfma_f32_32x32x16_bf16 v[16:31], v[78:81], v[98:101], v[16:31]
	v_mfma_f32_32x32x16_bf16 v[32:47], v[66:69], v[82:85], v[32:47]
	ds_read_b64_tr_b16 v[82:83], v191 offset:0x600
	ds_read_b64_tr_b16 v[84:85], v191 offset:0xe00
	v_mfma_f32_32x32x16_bf16 v[32:47], v[70:73], v[86:89], v[32:47]
	ds_read_b64_tr_b16 v[86:87], v191 offset:0x1600
	ds_read_b64_tr_b16 v[88:89], v191 offset:0x1e00
	v_mfma_f32_32x32x16_bf16 v[32:47], v[74:77], v[90:93], v[32:47]
	ds_read_b64_tr_b16 v[90:91], v191 offset:0x2600
	ds_read_b64_tr_b16 v[92:93], v191 offset:0x2e00
	ds_read_b64_tr_b16 v[98:99], v191 offset:0x3600
	ds_read_b64_tr_b16 v[100:101], v191 offset:0x3e00
	s_waitcnt lgkmcnt(0)
	v_mfma_f32_32x32x16_bf16 v[32:47], v[78:81], v[94:97], v[32:47]
	v_mfma_f32_32x32x16_bf16 v[48:63], v[66:69], v[82:85], v[48:63]
	v_mov_b32_e32 v65, v64
	s_nop 1
	v_permlane32_swap_b32_e32 v64, v65
	v_mfma_f32_32x32x16_bf16 v[48:63], v[70:73], v[86:89], v[48:63]
	v_mfma_f32_32x32x16_bf16 v[48:63], v[74:77], v[90:93], v[48:63]
	v_mfma_f32_32x32x16_bf16 v[48:63], v[78:81], v[98:101], v[48:63]
	s_and_saveexec_b64 s[60:61], s[0:1]
	s_cbranch_execz .LBB0_512
	v_add_f32_e32 v64, v64, v65
	ds_write_b32 v192, v64
	s_branch .LBB0_512

; __global__ void __launch_bounds__(NTHR, 2) fwd_kernel(Args args) {
	.amdhsa_kernel _Z10fwd_kernel4Args
		.amdhsa_group_segment_fixed_size 0
		.amdhsa_private_segment_fixed_size 0
		.amdhsa_kernarg_size 480
		.amdhsa_user_sgpr_count 2
		.amdhsa_user_sgpr_dispatch_ptr 0
		.amdhsa_user_sgpr_queue_ptr 0
		.amdhsa_user_sgpr_kernarg_segment_ptr 1
		.amdhsa_user_sgpr_dispatch_id 0
		.amdhsa_user_sgpr_kernarg_preload_length 0
		.amdhsa_user_sgpr_kernarg_preload_offset 0
		.amdhsa_user_sgpr_private_segment_size 0
		.amdhsa_uses_dynamic_stack 0
		.amdhsa_enable_private_segment 0
		.amdhsa_system_sgpr_workgroup_id_x 1
		.amdhsa_system_sgpr_workgroup_id_y 0
		.amdhsa_system_sgpr_workgroup_id_z 0
		.amdhsa_system_sgpr_workgroup_info 0
		.amdhsa_system_vgpr_workitem_id 2
		.amdhsa_next_free_vgpr 256
		.amdhsa_next_free_sgpr 102
		.amdhsa_accum_offset 256
		.amdhsa_reserve_vcc 1
		.amdhsa_float_round_mode_32 0
		.amdhsa_float_round_mode_16_64 0
		.amdhsa_float_denorm_mode_32 3
		.amdhsa_float_denorm_mode_16_64 3
		.amdhsa_dx10_clamp 1
		.amdhsa_ieee_mode 1
		.amdhsa_fp16_overflow 0
		.amdhsa_tg_split 0
		.amdhsa_exception_fp_ieee_invalid_op 0
		.amdhsa_exception_fp_denorm_src 0
		.amdhsa_exception_fp_ieee_div_zero 0
		.amdhsa_exception_fp_ieee_overflow 0
		.amdhsa_exception_fp_ieee_underflow 0
		.amdhsa_exception_fp_ieee_inexact 0
		.amdhsa_exception_int_div_zero 0
	.end_amdhsa_kernel

; __global__ void __launch_bounds__(NTHR, 2) fwd_kernel(Args args) {
amdhsa.kernels:
  - .agpr_count:     0
    .args:
      - .offset:         0
        .size:           224
        .value_kind:     by_value
      - .offset:         224
        .size:           4
        .value_kind:     hidden_block_count_x
      - .offset:         228
        .size:           4
        .value_kind:     hidden_block_count_y
      - .offset:         232
        .size:           4
        .value_kind:     hidden_block_count_z
      - .offset:         236
        .size:           2
        .value_kind:     hidden_group_size_x
      - .offset:         238
        .size:           2
        .value_kind:     hidden_group_size_y
      - .offset:         240
        .size:           2
        .value_kind:     hidden_group_size_z
      - .offset:         242
        .size:           2
        .value_kind:     hidden_remainder_x
      - .offset:         244
        .size:           2
        .value_kind:     hidden_remainder_y
      - .offset:         246
        .size:           2
        .value_kind:     hidden_remainder_z
      - .offset:         264
        .size:           8
        .value_kind:     hidden_global_offset_x
      - .offset:         272
        .size:           8
        .value_kind:     hidden_global_offset_y
      - .offset:         280
        .size:           8
        .value_kind:     hidden_global_offset_z
      - .offset:         288
        .size:           2
        .value_kind:     hidden_grid_dims
      - .offset:         312
        .size:           8
        .value_kind:     hidden_multigrid_sync_arg
      - .offset:         344
        .size:           4
        .value_kind:     hidden_dynamic_lds_size
    .group_segment_fixed_size: 0
    .kernarg_segment_align: 8
    .kernarg_segment_size: 480
    .language:       OpenCL C
    .language_version:
      - 2
      - 0
    .max_flat_workgroup_size: 512
    .name:           _Z10fwd_kernel4Args
    .private_segment_fixed_size: 0
    .sgpr_count:     108
    .sgpr_spill_count: 19
    .symbol:         _Z10fwd_kernel4Args.kd
    .uniform_work_group_size: 1
    .uses_dynamic_stack: false
    .vgpr_count:     256
    .vgpr_spill_count: 0
    .wavefront_size: 64
